# pipelined rmsnorm passes (3-deep row prefetch, DPP wave reduction) for the three in-loop norm phases, on top of v41
# speedup vs baseline: 1.0319x; 1.0001x over previous
.LBB0_144:
	s_andn2_b64 vcc, exec, s[0:1]
	s_cbranch_vccnz .LBB0_199
	s_mov_b64 s[2:3], s[84:85]
	v_mov_b32_e32 v0, v196
	v_mov_b32_e32 v2, v196
	v_readlane_b32 s0, v249, 1
	s_nop 0
	s_cmpk_lg_u32 s0, 0x200
	s_cbranch_scc1 .Lnrm_mix_orig
	v_readlane_b32 s0, v249, 5
	v_lshrrev_b32_e32 v68, 6, v196
	s_load_dwordx4 s[28:31], s[84:85], 0x130
	s_load_dwordx2 s[32:33], s[84:85], 0x48
	v_and_b32_e32 v69, 63, v196
	v_readfirstlane_b32 s1, v68
	v_lshlrev_b32_e32 v70, 4, v69
	v_lshlrev_b32_e32 v71, 3, v69
	s_add_i32 s0, s0, s1
	s_waitcnt lgkmcnt(0)
	s_add_u32 s32, s32, 0x1000
	s_addc_u32 s33, s33, 0
	global_load_dwordx4 v[4:7], v70, s[32:33]
	global_load_dwordx4 v[8:11], v70, s[32:33] offset:1024
	global_load_dwordx4 v[12:15], v70, s[32:33] offset:2048
	global_load_dwordx4 v[16:19], v70, s[32:33] offset:3072
	s_lshl_b32 s2, s0, 12
	s_add_u32 s34, s28, s2
	s_addc_u32 s35, s29, 0
	s_lshl_b32 s2, s0, 11
	s_add_u32 s36, s30, s2
	s_addc_u32 s37, s31, 0
	global_load_dwordx4 v[20:23], v70, s[34:35]
	global_load_dwordx4 v[24:27], v70, s[34:35] offset:1024
	global_load_dwordx4 v[28:31], v70, s[34:35] offset:2048
	global_load_dwordx4 v[32:35], v70, s[34:35] offset:3072
	s_add_u32 s34, s34, 0x800000
	s_addc_u32 s35, s35, 0
	global_load_dwordx4 v[36:39], v70, s[34:35]
	global_load_dwordx4 v[40:43], v70, s[34:35] offset:1024
	global_load_dwordx4 v[44:47], v70, s[34:35] offset:2048
	global_load_dwordx4 v[48:51], v70, s[34:35] offset:3072
	s_add_u32 s34, s34, 0x800000
	s_addc_u32 s35, s35, 0
	global_load_dwordx4 v[52:55], v70, s[34:35]
	global_load_dwordx4 v[56:59], v70, s[34:35] offset:1024
	global_load_dwordx4 v[60:63], v70, s[34:35] offset:2048
	global_load_dwordx4 v[64:67], v70, s[34:35] offset:3072
	s_add_u32 s34, s34, 0x800000
	s_addc_u32 s35, s35, 0
	s_waitcnt vmcnt(8)
	v_mul_f32_e32 v72, v20, v20
	v_mul_f32_e32 v73, v21, v21
	v_fmac_f32_e32 v72, v22, v22
	v_fmac_f32_e32 v73, v23, v23
	v_fmac_f32_e32 v72, v24, v24
	v_fmac_f32_e32 v73, v25, v25
	v_fmac_f32_e32 v72, v26, v26
	v_fmac_f32_e32 v73, v27, v27
	v_fmac_f32_e32 v72, v28, v28
	v_fmac_f32_e32 v73, v29, v29
	v_fmac_f32_e32 v72, v30, v30
	v_fmac_f32_e32 v73, v31, v31
	v_fmac_f32_e32 v72, v32, v32
	v_fmac_f32_e32 v73, v33, v33
	v_fmac_f32_e32 v72, v34, v34
	v_fmac_f32_e32 v73, v35, v35
	v_add_f32_e32 v72, v72, v73
	s_nop 1
	v_add_f32_dpp v72, v72, v72 quad_perm:[1,0,3,2] row_mask:0xf bank_mask:0xf
	s_nop 1
	v_add_f32_dpp v72, v72, v72 quad_perm:[2,3,0,1] row_mask:0xf bank_mask:0xf
	s_nop 1
	v_add_f32_dpp v72, v72, v72 row_half_mirror row_mask:0xf bank_mask:0xf
	s_nop 1
	v_add_f32_dpp v72, v72, v72 row_mirror row_mask:0xf bank_mask:0xf
	s_nop 1
	v_add_f32_dpp v72, v72, v72 row_bcast:15 row_mask:0xa bank_mask:0xf
	s_nop 1
	v_add_f32_dpp v72, v72, v72 row_bcast:31 row_mask:0xc bank_mask:0xf
	s_nop 1
	v_readlane_b32 s3, v72, 63
	s_nop 1
	v_mov_b32_e32 v72, s3
	v_fmamk_f32 v72, v72, 0x3a800000, v172
	v_rsq_f32_e32 v72, v72
	s_nop 0
	v_mul_f32_e32 v20, v20, v72
	v_mul_f32_e32 v21, v21, v72
	v_mul_f32_e32 v22, v22, v72
	v_mul_f32_e32 v23, v23, v72
	v_mul_f32_e32 v20, v4, v20
	v_mul_f32_e32 v21, v5, v21
	v_mul_f32_e32 v22, v6, v22
	v_mul_f32_e32 v23, v7, v23
	v_cvt_pk_bf16_f32 v74, v20, v21
	v_cvt_pk_bf16_f32 v75, v22, v23
	global_store_dwordx2 v71, v[74:75], s[36:37]
	v_mul_f32_e32 v24, v24, v72
	v_mul_f32_e32 v25, v25, v72
	v_mul_f32_e32 v26, v26, v72
	v_mul_f32_e32 v27, v27, v72
	v_mul_f32_e32 v24, v8, v24
	v_mul_f32_e32 v25, v9, v25
	v_mul_f32_e32 v26, v10, v26
	v_mul_f32_e32 v27, v11, v27
	v_cvt_pk_bf16_f32 v76, v24, v25
	v_cvt_pk_bf16_f32 v77, v26, v27
	global_store_dwordx2 v71, v[76:77], s[36:37] offset:512
	v_mul_f32_e32 v28, v28, v72
	v_mul_f32_e32 v29, v29, v72
	v_mul_f32_e32 v30, v30, v72
	v_mul_f32_e32 v31, v31, v72
	v_mul_f32_e32 v28, v12, v28
	v_mul_f32_e32 v29, v13, v29
	v_mul_f32_e32 v30, v14, v30
	v_mul_f32_e32 v31, v15, v31
	v_cvt_pk_bf16_f32 v78, v28, v29
	v_cvt_pk_bf16_f32 v79, v30, v31
	global_store_dwordx2 v71, v[78:79], s[36:37] offset:1024
	v_mul_f32_e32 v32, v32, v72
	v_mul_f32_e32 v33, v33, v72
	v_mul_f32_e32 v34, v34, v72
	v_mul_f32_e32 v35, v35, v72
	v_mul_f32_e32 v32, v16, v32
	v_mul_f32_e32 v33, v17, v33
	v_mul_f32_e32 v34, v18, v34
	v_mul_f32_e32 v35, v19, v35
	v_cvt_pk_bf16_f32 v80, v32, v33
	v_cvt_pk_bf16_f32 v81, v34, v35
	global_store_dwordx2 v71, v[80:81], s[36:37] offset:1536
	s_add_u32 s36, s36, 0x400000
	s_addc_u32 s37, s37, 0
	global_load_dwordx4 v[20:23], v70, s[34:35]
	global_load_dwordx4 v[24:27], v70, s[34:35] offset:1024
	global_load_dwordx4 v[28:31], v70, s[34:35] offset:2048
	global_load_dwordx4 v[32:35], v70, s[34:35] offset:3072
	s_add_u32 s34, s34, 0x800000
	s_addc_u32 s35, s35, 0
	s_waitcnt vmcnt(12)
	v_mul_f32_e32 v72, v36, v36
	v_mul_f32_e32 v73, v37, v37
	v_fmac_f32_e32 v72, v38, v38
	v_fmac_f32_e32 v73, v39, v39
	v_fmac_f32_e32 v72, v40, v40
	v_fmac_f32_e32 v73, v41, v41
	v_fmac_f32_e32 v72, v42, v42
	v_fmac_f32_e32 v73, v43, v43
	v_fmac_f32_e32 v72, v44, v44
	v_fmac_f32_e32 v73, v45, v45
	v_fmac_f32_e32 v72, v46, v46
	v_fmac_f32_e32 v73, v47, v47
	v_fmac_f32_e32 v72, v48, v48
	v_fmac_f32_e32 v73, v49, v49
	v_fmac_f32_e32 v72, v50, v50
	v_fmac_f32_e32 v73, v51, v51
	v_add_f32_e32 v72, v72, v73
	s_nop 1
	v_add_f32_dpp v72, v72, v72 quad_perm:[1,0,3,2] row_mask:0xf bank_mask:0xf
	s_nop 1
	v_add_f32_dpp v72, v72, v72 quad_perm:[2,3,0,1] row_mask:0xf bank_mask:0xf
	s_nop 1
	v_add_f32_dpp v72, v72, v72 row_half_mirror row_mask:0xf bank_mask:0xf
	s_nop 1
	v_add_f32_dpp v72, v72, v72 row_mirror row_mask:0xf bank_mask:0xf
	s_nop 1
	v_add_f32_dpp v72, v72, v72 row_bcast:15 row_mask:0xa bank_mask:0xf
	s_nop 1
	v_add_f32_dpp v72, v72, v72 row_bcast:31 row_mask:0xc bank_mask:0xf
	s_nop 1
	v_readlane_b32 s3, v72, 63
	s_nop 1
	v_mov_b32_e32 v72, s3
	v_fmamk_f32 v72, v72, 0x3a800000, v172
	v_rsq_f32_e32 v72, v72
	s_nop 0
	v_mul_f32_e32 v36, v36, v72
	v_mul_f32_e32 v37, v37, v72
	v_mul_f32_e32 v38, v38, v72
	v_mul_f32_e32 v39, v39, v72
	v_mul_f32_e32 v36, v4, v36
	v_mul_f32_e32 v37, v5, v37
	v_mul_f32_e32 v38, v6, v38
	v_mul_f32_e32 v39, v7, v39
	v_cvt_pk_bf16_f32 v74, v36, v37
	v_cvt_pk_bf16_f32 v75, v38, v39
	global_store_dwordx2 v71, v[74:75], s[36:37]
	v_mul_f32_e32 v40, v40, v72
	v_mul_f32_e32 v41, v41, v72
	v_mul_f32_e32 v42, v42, v72
	v_mul_f32_e32 v43, v43, v72
	v_mul_f32_e32 v40, v8, v40
	v_mul_f32_e32 v41, v9, v41
	v_mul_f32_e32 v42, v10, v42
	v_mul_f32_e32 v43, v11, v43
	v_cvt_pk_bf16_f32 v76, v40, v41
	v_cvt_pk_bf16_f32 v77, v42, v43
	global_store_dwordx2 v71, v[76:77], s[36:37] offset:512
	v_mul_f32_e32 v44, v44, v72
	v_mul_f32_e32 v45, v45, v72
	v_mul_f32_e32 v46, v46, v72
	v_mul_f32_e32 v47, v47, v72
	v_mul_f32_e32 v44, v12, v44
	v_mul_f32_e32 v45, v13, v45
	v_mul_f32_e32 v46, v14, v46
	v_mul_f32_e32 v47, v15, v47
	v_cvt_pk_bf16_f32 v78, v44, v45
	v_cvt_pk_bf16_f32 v79, v46, v47
	global_store_dwordx2 v71, v[78:79], s[36:37] offset:1024
	v_mul_f32_e32 v48, v48, v72
	v_mul_f32_e32 v49, v49, v72
	v_mul_f32_e32 v50, v50, v72
	v_mul_f32_e32 v51, v51, v72
	v_mul_f32_e32 v48, v16, v48
	v_mul_f32_e32 v49, v17, v49
	v_mul_f32_e32 v50, v18, v50
	v_mul_f32_e32 v51, v19, v51
	v_cvt_pk_bf16_f32 v80, v48, v49
	v_cvt_pk_bf16_f32 v81, v50, v51
	global_store_dwordx2 v71, v[80:81], s[36:37] offset:1536
	s_add_u32 s36, s36, 0x400000
	s_addc_u32 s37, s37, 0
	global_load_dwordx4 v[36:39], v70, s[34:35]
	global_load_dwordx4 v[40:43], v70, s[34:35] offset:1024
	global_load_dwordx4 v[44:47], v70, s[34:35] offset:2048
	global_load_dwordx4 v[48:51], v70, s[34:35] offset:3072
	s_add_u32 s34, s34, 0x800000
	s_addc_u32 s35, s35, 0
	s_waitcnt vmcnt(16)
	v_mul_f32_e32 v72, v52, v52
	v_mul_f32_e32 v73, v53, v53
	v_fmac_f32_e32 v72, v54, v54
	v_fmac_f32_e32 v73, v55, v55
	v_fmac_f32_e32 v72, v56, v56
	v_fmac_f32_e32 v73, v57, v57
	v_fmac_f32_e32 v72, v58, v58
	v_fmac_f32_e32 v73, v59, v59
	v_fmac_f32_e32 v72, v60, v60
	v_fmac_f32_e32 v73, v61, v61
	v_fmac_f32_e32 v72, v62, v62
	v_fmac_f32_e32 v73, v63, v63
	v_fmac_f32_e32 v72, v64, v64
	v_fmac_f32_e32 v73, v65, v65
	v_fmac_f32_e32 v72, v66, v66
	v_fmac_f32_e32 v73, v67, v67
	v_add_f32_e32 v72, v72, v73
	s_nop 1
	v_add_f32_dpp v72, v72, v72 quad_perm:[1,0,3,2] row_mask:0xf bank_mask:0xf
	s_nop 1
	v_add_f32_dpp v72, v72, v72 quad_perm:[2,3,0,1] row_mask:0xf bank_mask:0xf
	s_nop 1
	v_add_f32_dpp v72, v72, v72 row_half_mirror row_mask:0xf bank_mask:0xf
	s_nop 1
	v_add_f32_dpp v72, v72, v72 row_mirror row_mask:0xf bank_mask:0xf
	s_nop 1
	v_add_f32_dpp v72, v72, v72 row_bcast:15 row_mask:0xa bank_mask:0xf
	s_nop 1
	v_add_f32_dpp v72, v72, v72 row_bcast:31 row_mask:0xc bank_mask:0xf
	s_nop 1
	v_readlane_b32 s3, v72, 63
	s_nop 1
	v_mov_b32_e32 v72, s3
	v_fmamk_f32 v72, v72, 0x3a800000, v172
	v_rsq_f32_e32 v72, v72
	s_nop 0
	v_mul_f32_e32 v52, v52, v72
	v_mul_f32_e32 v53, v53, v72
	v_mul_f32_e32 v54, v54, v72
	v_mul_f32_e32 v55, v55, v72
	v_mul_f32_e32 v52, v4, v52
	v_mul_f32_e32 v53, v5, v53
	v_mul_f32_e32 v54, v6, v54
	v_mul_f32_e32 v55, v7, v55
	v_cvt_pk_bf16_f32 v74, v52, v53
	v_cvt_pk_bf16_f32 v75, v54, v55
	global_store_dwordx2 v71, v[74:75], s[36:37]
	v_mul_f32_e32 v56, v56, v72
	v_mul_f32_e32 v57, v57, v72
	v_mul_f32_e32 v58, v58, v72
	v_mul_f32_e32 v59, v59, v72
	v_mul_f32_e32 v56, v8, v56
	v_mul_f32_e32 v57, v9, v57
	v_mul_f32_e32 v58, v10, v58
	v_mul_f32_e32 v59, v11, v59
	v_cvt_pk_bf16_f32 v76, v56, v57
	v_cvt_pk_bf16_f32 v77, v58, v59
	global_store_dwordx2 v71, v[76:77], s[36:37] offset:512
	v_mul_f32_e32 v60, v60, v72
	v_mul_f32_e32 v61, v61, v72
	v_mul_f32_e32 v62, v62, v72
	v_mul_f32_e32 v63, v63, v72
	v_mul_f32_e32 v60, v12, v60
	v_mul_f32_e32 v61, v13, v61
	v_mul_f32_e32 v62, v14, v62
	v_mul_f32_e32 v63, v15, v63
	v_cvt_pk_bf16_f32 v78, v60, v61
	v_cvt_pk_bf16_f32 v79, v62, v63
	global_store_dwordx2 v71, v[78:79], s[36:37] offset:1024
	v_mul_f32_e32 v64, v64, v72
	v_mul_f32_e32 v65, v65, v72
	v_mul_f32_e32 v66, v66, v72
	v_mul_f32_e32 v67, v67, v72
	v_mul_f32_e32 v64, v16, v64
	v_mul_f32_e32 v65, v17, v65
	v_mul_f32_e32 v66, v18, v66
	v_mul_f32_e32 v67, v19, v67
	v_cvt_pk_bf16_f32 v80, v64, v65
	v_cvt_pk_bf16_f32 v81, v66, v67
	global_store_dwordx2 v71, v[80:81], s[36:37] offset:1536
	s_add_u32 s36, s36, 0x400000
	s_addc_u32 s37, s37, 0
	global_load_dwordx4 v[52:55], v70, s[34:35]
	global_load_dwordx4 v[56:59], v70, s[34:35] offset:1024
	global_load_dwordx4 v[60:63], v70, s[34:35] offset:2048
	global_load_dwordx4 v[64:67], v70, s[34:35] offset:3072
	s_add_u32 s34, s34, 0x800000
	s_addc_u32 s35, s35, 0
	s_waitcnt vmcnt(16)
	v_mul_f32_e32 v72, v20, v20
	v_mul_f32_e32 v73, v21, v21
	v_fmac_f32_e32 v72, v22, v22
	v_fmac_f32_e32 v73, v23, v23
	v_fmac_f32_e32 v72, v24, v24
	v_fmac_f32_e32 v73, v25, v25
	v_fmac_f32_e32 v72, v26, v26
	v_fmac_f32_e32 v73, v27, v27
	v_fmac_f32_e32 v72, v28, v28
	v_fmac_f32_e32 v73, v29, v29
	v_fmac_f32_e32 v72, v30, v30
	v_fmac_f32_e32 v73, v31, v31
	v_fmac_f32_e32 v72, v32, v32
	v_fmac_f32_e32 v73, v33, v33
	v_fmac_f32_e32 v72, v34, v34
	v_fmac_f32_e32 v73, v35, v35
	v_add_f32_e32 v72, v72, v73
	s_nop 1
	v_add_f32_dpp v72, v72, v72 quad_perm:[1,0,3,2] row_mask:0xf bank_mask:0xf
	s_nop 1
	v_add_f32_dpp v72, v72, v72 quad_perm:[2,3,0,1] row_mask:0xf bank_mask:0xf
	s_nop 1
	v_add_f32_dpp v72, v72, v72 row_half_mirror row_mask:0xf bank_mask:0xf
	s_nop 1
	v_add_f32_dpp v72, v72, v72 row_mirror row_mask:0xf bank_mask:0xf
	s_nop 1
	v_add_f32_dpp v72, v72, v72 row_bcast:15 row_mask:0xa bank_mask:0xf
	s_nop 1
	v_add_f32_dpp v72, v72, v72 row_bcast:31 row_mask:0xc bank_mask:0xf
	s_nop 1
	v_readlane_b32 s3, v72, 63
	s_nop 1
	v_mov_b32_e32 v72, s3
	v_fmamk_f32 v72, v72, 0x3a800000, v172
	v_rsq_f32_e32 v72, v72
	s_nop 0
	v_mul_f32_e32 v20, v20, v72
	v_mul_f32_e32 v21, v21, v72
	v_mul_f32_e32 v22, v22, v72
	v_mul_f32_e32 v23, v23, v72
	v_mul_f32_e32 v20, v4, v20
	v_mul_f32_e32 v21, v5, v21
	v_mul_f32_e32 v22, v6, v22
	v_mul_f32_e32 v23, v7, v23
	v_cvt_pk_bf16_f32 v74, v20, v21
	v_cvt_pk_bf16_f32 v75, v22, v23
	global_store_dwordx2 v71, v[74:75], s[36:37]
	v_mul_f32_e32 v24, v24, v72
	v_mul_f32_e32 v25, v25, v72
	v_mul_f32_e32 v26, v26, v72
	v_mul_f32_e32 v27, v27, v72
	v_mul_f32_e32 v24, v8, v24
	v_mul_f32_e32 v25, v9, v25
	v_mul_f32_e32 v26, v10, v26
	v_mul_f32_e32 v27, v11, v27
	v_cvt_pk_bf16_f32 v76, v24, v25
	v_cvt_pk_bf16_f32 v77, v26, v27
	global_store_dwordx2 v71, v[76:77], s[36:37] offset:512
	v_mul_f32_e32 v28, v28, v72
	v_mul_f32_e32 v29, v29, v72
	v_mul_f32_e32 v30, v30, v72
	v_mul_f32_e32 v31, v31, v72
	v_mul_f32_e32 v28, v12, v28
	v_mul_f32_e32 v29, v13, v29
	v_mul_f32_e32 v30, v14, v30
	v_mul_f32_e32 v31, v15, v31
	v_cvt_pk_bf16_f32 v78, v28, v29
	v_cvt_pk_bf16_f32 v79, v30, v31
	global_store_dwordx2 v71, v[78:79], s[36:37] offset:1024
	v_mul_f32_e32 v32, v32, v72
	v_mul_f32_e32 v33, v33, v72
	v_mul_f32_e32 v34, v34, v72
	v_mul_f32_e32 v35, v35, v72
	v_mul_f32_e32 v32, v16, v32
	v_mul_f32_e32 v33, v17, v33
	v_mul_f32_e32 v34, v18, v34
	v_mul_f32_e32 v35, v19, v35
	v_cvt_pk_bf16_f32 v80, v32, v33
	v_cvt_pk_bf16_f32 v81, v34, v35
	global_store_dwordx2 v71, v[80:81], s[36:37] offset:1536
	s_add_u32 s36, s36, 0x400000
	s_addc_u32 s37, s37, 0
	global_load_dwordx4 v[20:23], v70, s[34:35]
	global_load_dwordx4 v[24:27], v70, s[34:35] offset:1024
	global_load_dwordx4 v[28:31], v70, s[34:35] offset:2048
	global_load_dwordx4 v[32:35], v70, s[34:35] offset:3072
	s_add_u32 s34, s34, 0x800000
	s_addc_u32 s35, s35, 0
	s_waitcnt vmcnt(16)
	v_mul_f32_e32 v72, v36, v36
	v_mul_f32_e32 v73, v37, v37
	v_fmac_f32_e32 v72, v38, v38
	v_fmac_f32_e32 v73, v39, v39
	v_fmac_f32_e32 v72, v40, v40
	v_fmac_f32_e32 v73, v41, v41
	v_fmac_f32_e32 v72, v42, v42
	v_fmac_f32_e32 v73, v43, v43
	v_fmac_f32_e32 v72, v44, v44
	v_fmac_f32_e32 v73, v45, v45
	v_fmac_f32_e32 v72, v46, v46
	v_fmac_f32_e32 v73, v47, v47
	v_fmac_f32_e32 v72, v48, v48
	v_fmac_f32_e32 v73, v49, v49
	v_fmac_f32_e32 v72, v50, v50
	v_fmac_f32_e32 v73, v51, v51
	v_add_f32_e32 v72, v72, v73
	s_nop 1
	v_add_f32_dpp v72, v72, v72 quad_perm:[1,0,3,2] row_mask:0xf bank_mask:0xf
	s_nop 1
	v_add_f32_dpp v72, v72, v72 quad_perm:[2,3,0,1] row_mask:0xf bank_mask:0xf
	s_nop 1
	v_add_f32_dpp v72, v72, v72 row_half_mirror row_mask:0xf bank_mask:0xf
	s_nop 1
	v_add_f32_dpp v72, v72, v72 row_mirror row_mask:0xf bank_mask:0xf
	s_nop 1
	v_add_f32_dpp v72, v72, v72 row_bcast:15 row_mask:0xa bank_mask:0xf
	s_nop 1
	v_add_f32_dpp v72, v72, v72 row_bcast:31 row_mask:0xc bank_mask:0xf
	s_nop 1
	v_readlane_b32 s3, v72, 63
	s_nop 1
	v_mov_b32_e32 v72, s3
	v_fmamk_f32 v72, v72, 0x3a800000, v172
	v_rsq_f32_e32 v72, v72
	s_nop 0
	v_mul_f32_e32 v36, v36, v72
	v_mul_f32_e32 v37, v37, v72
	v_mul_f32_e32 v38, v38, v72
	v_mul_f32_e32 v39, v39, v72
	v_mul_f32_e32 v36, v4, v36
	v_mul_f32_e32 v37, v5, v37
	v_mul_f32_e32 v38, v6, v38
	v_mul_f32_e32 v39, v7, v39
	v_cvt_pk_bf16_f32 v74, v36, v37
	v_cvt_pk_bf16_f32 v75, v38, v39
	global_store_dwordx2 v71, v[74:75], s[36:37]
	v_mul_f32_e32 v40, v40, v72
	v_mul_f32_e32 v41, v41, v72
	v_mul_f32_e32 v42, v42, v72
	v_mul_f32_e32 v43, v43, v72
	v_mul_f32_e32 v40, v8, v40
	v_mul_f32_e32 v41, v9, v41
	v_mul_f32_e32 v42, v10, v42
	v_mul_f32_e32 v43, v11, v43
	v_cvt_pk_bf16_f32 v76, v40, v41
	v_cvt_pk_bf16_f32 v77, v42, v43
	global_store_dwordx2 v71, v[76:77], s[36:37] offset:512
	v_mul_f32_e32 v44, v44, v72
	v_mul_f32_e32 v45, v45, v72
	v_mul_f32_e32 v46, v46, v72
	v_mul_f32_e32 v47, v47, v72
	v_mul_f32_e32 v44, v12, v44
	v_mul_f32_e32 v45, v13, v45
	v_mul_f32_e32 v46, v14, v46
	v_mul_f32_e32 v47, v15, v47
	v_cvt_pk_bf16_f32 v78, v44, v45
	v_cvt_pk_bf16_f32 v79, v46, v47
	global_store_dwordx2 v71, v[78:79], s[36:37] offset:1024
	v_mul_f32_e32 v48, v48, v72
	v_mul_f32_e32 v49, v49, v72
	v_mul_f32_e32 v50, v50, v72
	v_mul_f32_e32 v51, v51, v72
	v_mul_f32_e32 v48, v16, v48
	v_mul_f32_e32 v49, v17, v49
	v_mul_f32_e32 v50, v18, v50
	v_mul_f32_e32 v51, v19, v51
	v_cvt_pk_bf16_f32 v80, v48, v49
	v_cvt_pk_bf16_f32 v81, v50, v51
	global_store_dwordx2 v71, v[80:81], s[36:37] offset:1536
	s_add_u32 s36, s36, 0x400000
	s_addc_u32 s37, s37, 0
	global_load_dwordx4 v[36:39], v70, s[34:35]
	global_load_dwordx4 v[40:43], v70, s[34:35] offset:1024
	global_load_dwordx4 v[44:47], v70, s[34:35] offset:2048
	global_load_dwordx4 v[48:51], v70, s[34:35] offset:3072
	s_add_u32 s34, s34, 0x800000
	s_addc_u32 s35, s35, 0
	s_waitcnt vmcnt(16)
	v_mul_f32_e32 v72, v52, v52
	v_mul_f32_e32 v73, v53, v53
	v_fmac_f32_e32 v72, v54, v54
	v_fmac_f32_e32 v73, v55, v55
	v_fmac_f32_e32 v72, v56, v56
	v_fmac_f32_e32 v73, v57, v57
	v_fmac_f32_e32 v72, v58, v58
	v_fmac_f32_e32 v73, v59, v59
	v_fmac_f32_e32 v72, v60, v60
	v_fmac_f32_e32 v73, v61, v61
	v_fmac_f32_e32 v72, v62, v62
	v_fmac_f32_e32 v73, v63, v63
	v_fmac_f32_e32 v72, v64, v64
	v_fmac_f32_e32 v73, v65, v65
	v_fmac_f32_e32 v72, v66, v66
	v_fmac_f32_e32 v73, v67, v67
	v_add_f32_e32 v72, v72, v73
	s_nop 1
	v_add_f32_dpp v72, v72, v72 quad_perm:[1,0,3,2] row_mask:0xf bank_mask:0xf
	s_nop 1
	v_add_f32_dpp v72, v72, v72 quad_perm:[2,3,0,1] row_mask:0xf bank_mask:0xf
	s_nop 1
	v_add_f32_dpp v72, v72, v72 row_half_mirror row_mask:0xf bank_mask:0xf
	s_nop 1
	v_add_f32_dpp v72, v72, v72 row_mirror row_mask:0xf bank_mask:0xf
	s_nop 1
	v_add_f32_dpp v72, v72, v72 row_bcast:15 row_mask:0xa bank_mask:0xf
	s_nop 1
	v_add_f32_dpp v72, v72, v72 row_bcast:31 row_mask:0xc bank_mask:0xf
	s_nop 1
	v_readlane_b32 s3, v72, 63
	s_nop 1
	v_mov_b32_e32 v72, s3
	v_fmamk_f32 v72, v72, 0x3a800000, v172
	v_rsq_f32_e32 v72, v72
	s_nop 0
	v_mul_f32_e32 v52, v52, v72
	v_mul_f32_e32 v53, v53, v72
	v_mul_f32_e32 v54, v54, v72
	v_mul_f32_e32 v55, v55, v72
	v_mul_f32_e32 v52, v4, v52
	v_mul_f32_e32 v53, v5, v53
	v_mul_f32_e32 v54, v6, v54
	v_mul_f32_e32 v55, v7, v55
	v_cvt_pk_bf16_f32 v74, v52, v53
	v_cvt_pk_bf16_f32 v75, v54, v55
	global_store_dwordx2 v71, v[74:75], s[36:37]
	v_mul_f32_e32 v56, v56, v72
	v_mul_f32_e32 v57, v57, v72
	v_mul_f32_e32 v58, v58, v72
	v_mul_f32_e32 v59, v59, v72
	v_mul_f32_e32 v56, v8, v56
	v_mul_f32_e32 v57, v9, v57
	v_mul_f32_e32 v58, v10, v58
	v_mul_f32_e32 v59, v11, v59
	v_cvt_pk_bf16_f32 v76, v56, v57
	v_cvt_pk_bf16_f32 v77, v58, v59
	global_store_dwordx2 v71, v[76:77], s[36:37] offset:512
	v_mul_f32_e32 v60, v60, v72
	v_mul_f32_e32 v61, v61, v72
	v_mul_f32_e32 v62, v62, v72
	v_mul_f32_e32 v63, v63, v72
	v_mul_f32_e32 v60, v12, v60
	v_mul_f32_e32 v61, v13, v61
	v_mul_f32_e32 v62, v14, v62
	v_mul_f32_e32 v63, v15, v63
	v_cvt_pk_bf16_f32 v78, v60, v61
	v_cvt_pk_bf16_f32 v79, v62, v63
	global_store_dwordx2 v71, v[78:79], s[36:37] offset:1024
	v_mul_f32_e32 v64, v64, v72
	v_mul_f32_e32 v65, v65, v72
	v_mul_f32_e32 v66, v66, v72
	v_mul_f32_e32 v67, v67, v72
	v_mul_f32_e32 v64, v16, v64
	v_mul_f32_e32 v65, v17, v65
	v_mul_f32_e32 v66, v18, v66
	v_mul_f32_e32 v67, v19, v67
	v_cvt_pk_bf16_f32 v80, v64, v65
	v_cvt_pk_bf16_f32 v81, v66, v67
	global_store_dwordx2 v71, v[80:81], s[36:37] offset:1536
	s_add_u32 s36, s36, 0x400000
	s_addc_u32 s37, s37, 0
	s_cmpk_lt_u32 s0, 0x100
	s_cbranch_scc0 .Lnrm_mix_nol8
	global_load_dwordx4 v[52:55], v70, s[34:35]
	global_load_dwordx4 v[56:59], v70, s[34:35] offset:1024
	global_load_dwordx4 v[60:63], v70, s[34:35] offset:2048
	global_load_dwordx4 v[64:67], v70, s[34:35] offset:3072
	s_add_u32 s34, s34, 0x800000
	s_addc_u32 s35, s35, 0
.Lnrm_mix_nol8:
	s_waitcnt vmcnt(12)
	v_mul_f32_e32 v72, v20, v20
	v_mul_f32_e32 v73, v21, v21
	v_fmac_f32_e32 v72, v22, v22
	v_fmac_f32_e32 v73, v23, v23
	v_fmac_f32_e32 v72, v24, v24
	v_fmac_f32_e32 v73, v25, v25
	v_fmac_f32_e32 v72, v26, v26
	v_fmac_f32_e32 v73, v27, v27
	v_fmac_f32_e32 v72, v28, v28
	v_fmac_f32_e32 v73, v29, v29
	v_fmac_f32_e32 v72, v30, v30
	v_fmac_f32_e32 v73, v31, v31
	v_fmac_f32_e32 v72, v32, v32
	v_fmac_f32_e32 v73, v33, v33
	v_fmac_f32_e32 v72, v34, v34
	v_fmac_f32_e32 v73, v35, v35
	v_add_f32_e32 v72, v72, v73
	s_nop 1
	v_add_f32_dpp v72, v72, v72 quad_perm:[1,0,3,2] row_mask:0xf bank_mask:0xf
	s_nop 1
	v_add_f32_dpp v72, v72, v72 quad_perm:[2,3,0,1] row_mask:0xf bank_mask:0xf
	s_nop 1
	v_add_f32_dpp v72, v72, v72 row_half_mirror row_mask:0xf bank_mask:0xf
	s_nop 1
	v_add_f32_dpp v72, v72, v72 row_mirror row_mask:0xf bank_mask:0xf
	s_nop 1
	v_add_f32_dpp v72, v72, v72 row_bcast:15 row_mask:0xa bank_mask:0xf
	s_nop 1
	v_add_f32_dpp v72, v72, v72 row_bcast:31 row_mask:0xc bank_mask:0xf
	s_nop 1
	v_readlane_b32 s3, v72, 63
	s_nop 1
	v_mov_b32_e32 v72, s3
	v_fmamk_f32 v72, v72, 0x3a800000, v172
	v_rsq_f32_e32 v72, v72
	s_nop 0
	v_mul_f32_e32 v20, v20, v72
	v_mul_f32_e32 v21, v21, v72
	v_mul_f32_e32 v22, v22, v72
	v_mul_f32_e32 v23, v23, v72
	v_mul_f32_e32 v20, v4, v20
	v_mul_f32_e32 v21, v5, v21
	v_mul_f32_e32 v22, v6, v22
	v_mul_f32_e32 v23, v7, v23
	v_cvt_pk_bf16_f32 v74, v20, v21
	v_cvt_pk_bf16_f32 v75, v22, v23
	global_store_dwordx2 v71, v[74:75], s[36:37]
	v_mul_f32_e32 v24, v24, v72
	v_mul_f32_e32 v25, v25, v72
	v_mul_f32_e32 v26, v26, v72
	v_mul_f32_e32 v27, v27, v72
	v_mul_f32_e32 v24, v8, v24
	v_mul_f32_e32 v25, v9, v25
	v_mul_f32_e32 v26, v10, v26
	v_mul_f32_e32 v27, v11, v27
	v_cvt_pk_bf16_f32 v76, v24, v25
	v_cvt_pk_bf16_f32 v77, v26, v27
	global_store_dwordx2 v71, v[76:77], s[36:37] offset:512
	v_mul_f32_e32 v28, v28, v72
	v_mul_f32_e32 v29, v29, v72
	v_mul_f32_e32 v30, v30, v72
	v_mul_f32_e32 v31, v31, v72
	v_mul_f32_e32 v28, v12, v28
	v_mul_f32_e32 v29, v13, v29
	v_mul_f32_e32 v30, v14, v30
	v_mul_f32_e32 v31, v15, v31
	v_cvt_pk_bf16_f32 v78, v28, v29
	v_cvt_pk_bf16_f32 v79, v30, v31
	global_store_dwordx2 v71, v[78:79], s[36:37] offset:1024
	v_mul_f32_e32 v32, v32, v72
	v_mul_f32_e32 v33, v33, v72
	v_mul_f32_e32 v34, v34, v72
	v_mul_f32_e32 v35, v35, v72
	v_mul_f32_e32 v32, v16, v32
	v_mul_f32_e32 v33, v17, v33
	v_mul_f32_e32 v34, v18, v34
	v_mul_f32_e32 v35, v19, v35
	v_cvt_pk_bf16_f32 v80, v32, v33
	v_cvt_pk_bf16_f32 v81, v34, v35
	global_store_dwordx2 v71, v[80:81], s[36:37] offset:1536
	s_add_u32 s36, s36, 0x400000
	s_addc_u32 s37, s37, 0
	s_waitcnt vmcnt(8)
	v_mul_f32_e32 v72, v36, v36
	v_mul_f32_e32 v73, v37, v37
	v_fmac_f32_e32 v72, v38, v38
	v_fmac_f32_e32 v73, v39, v39
	v_fmac_f32_e32 v72, v40, v40
	v_fmac_f32_e32 v73, v41, v41
	v_fmac_f32_e32 v72, v42, v42
	v_fmac_f32_e32 v73, v43, v43
	v_fmac_f32_e32 v72, v44, v44
	v_fmac_f32_e32 v73, v45, v45
	v_fmac_f32_e32 v72, v46, v46
	v_fmac_f32_e32 v73, v47, v47
	v_fmac_f32_e32 v72, v48, v48
	v_fmac_f32_e32 v73, v49, v49
	v_fmac_f32_e32 v72, v50, v50
	v_fmac_f32_e32 v73, v51, v51
	v_add_f32_e32 v72, v72, v73
	s_nop 1
	v_add_f32_dpp v72, v72, v72 quad_perm:[1,0,3,2] row_mask:0xf bank_mask:0xf
	s_nop 1
	v_add_f32_dpp v72, v72, v72 quad_perm:[2,3,0,1] row_mask:0xf bank_mask:0xf
	s_nop 1
	v_add_f32_dpp v72, v72, v72 row_half_mirror row_mask:0xf bank_mask:0xf
	s_nop 1
	v_add_f32_dpp v72, v72, v72 row_mirror row_mask:0xf bank_mask:0xf
	s_nop 1
	v_add_f32_dpp v72, v72, v72 row_bcast:15 row_mask:0xa bank_mask:0xf
	s_nop 1
	v_add_f32_dpp v72, v72, v72 row_bcast:31 row_mask:0xc bank_mask:0xf
	s_nop 1
	v_readlane_b32 s3, v72, 63
	s_nop 1
	v_mov_b32_e32 v72, s3
	v_fmamk_f32 v72, v72, 0x3a800000, v172
	v_rsq_f32_e32 v72, v72
	s_nop 0
	v_mul_f32_e32 v36, v36, v72
	v_mul_f32_e32 v37, v37, v72
	v_mul_f32_e32 v38, v38, v72
	v_mul_f32_e32 v39, v39, v72
	v_mul_f32_e32 v36, v4, v36
	v_mul_f32_e32 v37, v5, v37
	v_mul_f32_e32 v38, v6, v38
	v_mul_f32_e32 v39, v7, v39
	v_cvt_pk_bf16_f32 v74, v36, v37
	v_cvt_pk_bf16_f32 v75, v38, v39
	global_store_dwordx2 v71, v[74:75], s[36:37]
	v_mul_f32_e32 v40, v40, v72
	v_mul_f32_e32 v41, v41, v72
	v_mul_f32_e32 v42, v42, v72
	v_mul_f32_e32 v43, v43, v72
	v_mul_f32_e32 v40, v8, v40
	v_mul_f32_e32 v41, v9, v41
	v_mul_f32_e32 v42, v10, v42
	v_mul_f32_e32 v43, v11, v43
	v_cvt_pk_bf16_f32 v76, v40, v41
	v_cvt_pk_bf16_f32 v77, v42, v43
	global_store_dwordx2 v71, v[76:77], s[36:37] offset:512
	v_mul_f32_e32 v44, v44, v72
	v_mul_f32_e32 v45, v45, v72
	v_mul_f32_e32 v46, v46, v72
	v_mul_f32_e32 v47, v47, v72
	v_mul_f32_e32 v44, v12, v44
	v_mul_f32_e32 v45, v13, v45
	v_mul_f32_e32 v46, v14, v46
	v_mul_f32_e32 v47, v15, v47
	v_cvt_pk_bf16_f32 v78, v44, v45
	v_cvt_pk_bf16_f32 v79, v46, v47
	global_store_dwordx2 v71, v[78:79], s[36:37] offset:1024
	v_mul_f32_e32 v48, v48, v72
	v_mul_f32_e32 v49, v49, v72
	v_mul_f32_e32 v50, v50, v72
	v_mul_f32_e32 v51, v51, v72
	v_mul_f32_e32 v48, v16, v48
	v_mul_f32_e32 v49, v17, v49
	v_mul_f32_e32 v50, v18, v50
	v_mul_f32_e32 v51, v19, v51
	v_cvt_pk_bf16_f32 v80, v48, v49
	v_cvt_pk_bf16_f32 v81, v50, v51
	global_store_dwordx2 v71, v[80:81], s[36:37] offset:1536
	s_add_u32 s36, s36, 0x400000
	s_addc_u32 s37, s37, 0
	s_cmpk_lt_u32 s0, 0x100
	s_cbranch_scc0 .Lnrm_mix_done
	s_waitcnt vmcnt(8)
	v_mul_f32_e32 v72, v52, v52
	v_mul_f32_e32 v73, v53, v53
	v_fmac_f32_e32 v72, v54, v54
	v_fmac_f32_e32 v73, v55, v55
	v_fmac_f32_e32 v72, v56, v56
	v_fmac_f32_e32 v73, v57, v57
	v_fmac_f32_e32 v72, v58, v58
	v_fmac_f32_e32 v73, v59, v59
	v_fmac_f32_e32 v72, v60, v60
	v_fmac_f32_e32 v73, v61, v61
	v_fmac_f32_e32 v72, v62, v62
	v_fmac_f32_e32 v73, v63, v63
	v_fmac_f32_e32 v72, v64, v64
	v_fmac_f32_e32 v73, v65, v65
	v_fmac_f32_e32 v72, v66, v66
	v_fmac_f32_e32 v73, v67, v67
	v_add_f32_e32 v72, v72, v73
	s_nop 1
	v_add_f32_dpp v72, v72, v72 quad_perm:[1,0,3,2] row_mask:0xf bank_mask:0xf
	s_nop 1
	v_add_f32_dpp v72, v72, v72 quad_perm:[2,3,0,1] row_mask:0xf bank_mask:0xf
	s_nop 1
	v_add_f32_dpp v72, v72, v72 row_half_mirror row_mask:0xf bank_mask:0xf
	s_nop 1
	v_add_f32_dpp v72, v72, v72 row_mirror row_mask:0xf bank_mask:0xf
	s_nop 1
	v_add_f32_dpp v72, v72, v72 row_bcast:15 row_mask:0xa bank_mask:0xf
	s_nop 1
	v_add_f32_dpp v72, v72, v72 row_bcast:31 row_mask:0xc bank_mask:0xf
	s_nop 1
	v_readlane_b32 s3, v72, 63
	s_nop 1
	v_mov_b32_e32 v72, s3
	v_fmamk_f32 v72, v72, 0x3a800000, v172
	v_rsq_f32_e32 v72, v72
	s_nop 0
	v_mul_f32_e32 v52, v52, v72
	v_mul_f32_e32 v53, v53, v72
	v_mul_f32_e32 v54, v54, v72
	v_mul_f32_e32 v55, v55, v72
	v_mul_f32_e32 v52, v4, v52
	v_mul_f32_e32 v53, v5, v53
	v_mul_f32_e32 v54, v6, v54
	v_mul_f32_e32 v55, v7, v55
	v_cvt_pk_bf16_f32 v74, v52, v53
	v_cvt_pk_bf16_f32 v75, v54, v55
	global_store_dwordx2 v71, v[74:75], s[36:37]
	v_mul_f32_e32 v56, v56, v72
	v_mul_f32_e32 v57, v57, v72
	v_mul_f32_e32 v58, v58, v72
	v_mul_f32_e32 v59, v59, v72
	v_mul_f32_e32 v56, v8, v56
	v_mul_f32_e32 v57, v9, v57
	v_mul_f32_e32 v58, v10, v58
	v_mul_f32_e32 v59, v11, v59
	v_cvt_pk_bf16_f32 v76, v56, v57
	v_cvt_pk_bf16_f32 v77, v58, v59
	global_store_dwordx2 v71, v[76:77], s[36:37] offset:512
	v_mul_f32_e32 v60, v60, v72
	v_mul_f32_e32 v61, v61, v72
	v_mul_f32_e32 v62, v62, v72
	v_mul_f32_e32 v63, v63, v72
	v_mul_f32_e32 v60, v12, v60
	v_mul_f32_e32 v61, v13, v61
	v_mul_f32_e32 v62, v14, v62
	v_mul_f32_e32 v63, v15, v63
	v_cvt_pk_bf16_f32 v78, v60, v61
	v_cvt_pk_bf16_f32 v79, v62, v63
	global_store_dwordx2 v71, v[78:79], s[36:37] offset:1024
	v_mul_f32_e32 v64, v64, v72
	v_mul_f32_e32 v65, v65, v72
	v_mul_f32_e32 v66, v66, v72
	v_mul_f32_e32 v67, v67, v72
	v_mul_f32_e32 v64, v16, v64
	v_mul_f32_e32 v65, v17, v65
	v_mul_f32_e32 v66, v18, v66
	v_mul_f32_e32 v67, v19, v67
	v_cvt_pk_bf16_f32 v80, v64, v65
	v_cvt_pk_bf16_f32 v81, v66, v67
	global_store_dwordx2 v71, v[80:81], s[36:37] offset:1536
	s_add_u32 s36, s36, 0x400000
	s_addc_u32 s37, s37, 0
.Lnrm_mix_done:
	s_mov_b64 s[0:1], exec
	s_branch .LBB0_150
.Lnrm_mix_orig:
	v_readlane_b32 s0, v249, 5
	v_ashrrev_i32_e32 v2, 6, v2
	s_nop 0
	v_add_u32_e32 v18, s0, v2
	s_movk_i32 s0, 0x4100
	v_cmp_gt_i32_e32 vcc, s0, v18
	s_and_saveexec_b64 s[0:1], vcc
	s_cbranch_execz .LBB0_150
	s_load_dwordx2 s[4:5], s[2:3], 0x48
	v_lshlrev_b32_e32 v0, 2, v0
	v_and_b32_e32 v24, 0xfc, v0
	v_lshlrev_b32_e32 v0, 2, v24
	v_ashrrev_i32_e32 v19, 31, v18
	s_waitcnt lgkmcnt(0)
	v_lshl_add_u64 v[2:3], s[4:5], 0, v[0:1]
	s_mov_b64 s[4:5], 0x1000
	v_add_co_u32_e32 v10, vcc, s70, v2
	v_lshl_add_u64 v[14:15], v[2:3], 0, s[4:5]
	s_nop 0
	v_addc_co_u32_e32 v11, vcc, 0, v3, vcc
	global_load_dwordx4 v[2:5], v[14:15], off offset:1024
	global_load_dwordx4 v[6:9], v[14:15], off offset:2048
	s_nop 0
	global_load_dwordx4 v[10:13], v[10:11], off
	s_nop 0
	global_load_dwordx4 v[14:17], v[14:15], off offset:3072
	v_cmp_lt_i32_e32 vcc, v181, v180
	s_load_dwordx4 s[4:7], s[2:3], 0x130
	v_lshlrev_b64 v[22:23], 12, v[18:19]
	v_cndmask_b32_e32 v0, v178, v181, vcc
	v_cmp_lt_i32_e32 vcc, v173, v180
	v_lshlrev_b32_e32 v30, 2, v0
	s_waitcnt lgkmcnt(0)
	s_add_u32 s2, s4, 0x4000000
	v_cndmask_b32_e32 v0, v178, v173, vcc
	v_cmp_lt_i32_e32 vcc, v230, v180
	v_lshlrev_b32_e32 v31, 2, v0
	s_addc_u32 s3, s5, 0
	v_cndmask_b32_e32 v0, v178, v230, vcc
	v_cmp_lt_i32_e32 vcc, v248, v180
	v_lshlrev_b32_e32 v32, 2, v0
	v_lshl_add_u64 v[22:23], s[4:5], 0, v[22:23]
	v_cndmask_b32_e32 v0, v178, v248, vcc
	v_cmp_lt_i32_e32 vcc, v132, v180
	v_lshlrev_b32_e32 v33, 2, v0
	s_mov_b64 s[4:5], 0
	v_cndmask_b32_e32 v0, v178, v132, vcc
	v_cmp_lt_i32_e32 vcc, v186, v180
	v_lshlrev_b32_e32 v34, 2, v0
	v_mov_b32_e32 v25, v1
	v_cndmask_b32_e32 v0, v178, v186, vcc
	v_lshlrev_b32_e32 v35, 2, v0
	v_lshlrev_b32_e32 v0, 1, v24
	v_lshl_add_u64 v[20:21], s[6:7], 0, v[0:1]
	v_lshlrev_b32_e32 v24, 2, v24
	s_branch .LBB0_148

.LBB0_2296:
	s_or_b64 exec, exec, s[0:1]
	s_mov_b64 s[6:7], s[84:85]
	v_mov_b32_e32 v0, v196
	s_waitcnt lgkmcnt(0)
	v_mov_b32_e32 v2, v196
	s_barrier
	v_readlane_b32 s0, v249, 1
	s_nop 0
	s_cmpk_lg_u32 s0, 0x200
	s_cbranch_scc1 .Lnrm_ffn_orig
	v_readlane_b32 s0, v249, 5
	v_lshrrev_b32_e32 v68, 6, v196
	s_load_dwordx4 s[28:31], s[84:85], 0x130
	s_load_dwordx2 s[32:33], s[84:85], 0xa8
	v_and_b32_e32 v69, 63, v196
	v_readfirstlane_b32 s1, v68
	v_lshlrev_b32_e32 v70, 4, v69
	v_lshlrev_b32_e32 v71, 3, v69
	s_add_i32 s0, s0, s1
	s_waitcnt lgkmcnt(0)
	s_lshl_b32 s2, s72, 2
	s_add_u32 s32, s32, s2
	s_addc_u32 s33, s33, 0
	global_load_dwordx4 v[4:7], v70, s[32:33]
	global_load_dwordx4 v[8:11], v70, s[32:33] offset:1024
	global_load_dwordx4 v[12:15], v70, s[32:33] offset:2048
	global_load_dwordx4 v[16:19], v70, s[32:33] offset:3072
	s_lshl_b32 s2, s0, 12
	s_add_u32 s34, s28, s2
	s_addc_u32 s35, s29, 0
	s_lshl_b32 s2, s0, 11
	s_add_u32 s36, s30, s2
	s_addc_u32 s37, s31, 0
	global_load_dwordx4 v[20:23], v70, s[34:35]
	global_load_dwordx4 v[24:27], v70, s[34:35] offset:1024
	global_load_dwordx4 v[28:31], v70, s[34:35] offset:2048
	global_load_dwordx4 v[32:35], v70, s[34:35] offset:3072
	s_add_u32 s34, s34, 0x800000
	s_addc_u32 s35, s35, 0
	global_load_dwordx4 v[36:39], v70, s[34:35]
	global_load_dwordx4 v[40:43], v70, s[34:35] offset:1024
	global_load_dwordx4 v[44:47], v70, s[34:35] offset:2048
	global_load_dwordx4 v[48:51], v70, s[34:35] offset:3072
	s_add_u32 s34, s34, 0x800000
	s_addc_u32 s35, s35, 0
	global_load_dwordx4 v[52:55], v70, s[34:35]
	global_load_dwordx4 v[56:59], v70, s[34:35] offset:1024
	global_load_dwordx4 v[60:63], v70, s[34:35] offset:2048
	global_load_dwordx4 v[64:67], v70, s[34:35] offset:3072
	s_add_u32 s34, s34, 0x800000
	s_addc_u32 s35, s35, 0
	s_waitcnt vmcnt(8)
	v_mul_f32_e32 v72, v20, v20
	v_mul_f32_e32 v73, v21, v21
	v_fmac_f32_e32 v72, v22, v22
	v_fmac_f32_e32 v73, v23, v23
	v_fmac_f32_e32 v72, v24, v24
	v_fmac_f32_e32 v73, v25, v25
	v_fmac_f32_e32 v72, v26, v26
	v_fmac_f32_e32 v73, v27, v27
	v_fmac_f32_e32 v72, v28, v28
	v_fmac_f32_e32 v73, v29, v29
	v_fmac_f32_e32 v72, v30, v30
	v_fmac_f32_e32 v73, v31, v31
	v_fmac_f32_e32 v72, v32, v32
	v_fmac_f32_e32 v73, v33, v33
	v_fmac_f32_e32 v72, v34, v34
	v_fmac_f32_e32 v73, v35, v35
	v_add_f32_e32 v72, v72, v73
	s_nop 1
	v_add_f32_dpp v72, v72, v72 quad_perm:[1,0,3,2] row_mask:0xf bank_mask:0xf
	s_nop 1
	v_add_f32_dpp v72, v72, v72 quad_perm:[2,3,0,1] row_mask:0xf bank_mask:0xf
	s_nop 1
	v_add_f32_dpp v72, v72, v72 row_half_mirror row_mask:0xf bank_mask:0xf
	s_nop 1
	v_add_f32_dpp v72, v72, v72 row_mirror row_mask:0xf bank_mask:0xf
	s_nop 1
	v_add_f32_dpp v72, v72, v72 row_bcast:15 row_mask:0xa bank_mask:0xf
	s_nop 1
	v_add_f32_dpp v72, v72, v72 row_bcast:31 row_mask:0xc bank_mask:0xf
	s_nop 1
	v_readlane_b32 s3, v72, 63
	s_nop 1
	v_mov_b32_e32 v72, s3
	v_fmamk_f32 v72, v72, 0x3a800000, v172
	v_rsq_f32_e32 v72, v72
	s_nop 0
	v_mul_f32_e32 v20, v20, v72
	v_mul_f32_e32 v21, v21, v72
	v_mul_f32_e32 v22, v22, v72
	v_mul_f32_e32 v23, v23, v72
	v_mul_f32_e32 v20, v4, v20
	v_mul_f32_e32 v21, v5, v21
	v_mul_f32_e32 v22, v6, v22
	v_mul_f32_e32 v23, v7, v23
	v_cvt_pk_bf16_f32 v74, v20, v21
	v_cvt_pk_bf16_f32 v75, v22, v23
	global_store_dwordx2 v71, v[74:75], s[36:37]
	v_mul_f32_e32 v24, v24, v72
	v_mul_f32_e32 v25, v25, v72
	v_mul_f32_e32 v26, v26, v72
	v_mul_f32_e32 v27, v27, v72
	v_mul_f32_e32 v24, v8, v24
	v_mul_f32_e32 v25, v9, v25
	v_mul_f32_e32 v26, v10, v26
	v_mul_f32_e32 v27, v11, v27
	v_cvt_pk_bf16_f32 v76, v24, v25
	v_cvt_pk_bf16_f32 v77, v26, v27
	global_store_dwordx2 v71, v[76:77], s[36:37] offset:512
	v_mul_f32_e32 v28, v28, v72
	v_mul_f32_e32 v29, v29, v72
	v_mul_f32_e32 v30, v30, v72
	v_mul_f32_e32 v31, v31, v72
	v_mul_f32_e32 v28, v12, v28
	v_mul_f32_e32 v29, v13, v29
	v_mul_f32_e32 v30, v14, v30
	v_mul_f32_e32 v31, v15, v31
	v_cvt_pk_bf16_f32 v78, v28, v29
	v_cvt_pk_bf16_f32 v79, v30, v31
	global_store_dwordx2 v71, v[78:79], s[36:37] offset:1024
	v_mul_f32_e32 v32, v32, v72
	v_mul_f32_e32 v33, v33, v72
	v_mul_f32_e32 v34, v34, v72
	v_mul_f32_e32 v35, v35, v72
	v_mul_f32_e32 v32, v16, v32
	v_mul_f32_e32 v33, v17, v33
	v_mul_f32_e32 v34, v18, v34
	v_mul_f32_e32 v35, v19, v35
	v_cvt_pk_bf16_f32 v80, v32, v33
	v_cvt_pk_bf16_f32 v81, v34, v35
	global_store_dwordx2 v71, v[80:81], s[36:37] offset:1536
	s_add_u32 s36, s36, 0x400000
	s_addc_u32 s37, s37, 0
	global_load_dwordx4 v[20:23], v70, s[34:35]
	global_load_dwordx4 v[24:27], v70, s[34:35] offset:1024
	global_load_dwordx4 v[28:31], v70, s[34:35] offset:2048
	global_load_dwordx4 v[32:35], v70, s[34:35] offset:3072
	s_add_u32 s34, s34, 0x800000
	s_addc_u32 s35, s35, 0
	s_waitcnt vmcnt(12)
	v_mul_f32_e32 v72, v36, v36
	v_mul_f32_e32 v73, v37, v37
	v_fmac_f32_e32 v72, v38, v38
	v_fmac_f32_e32 v73, v39, v39
	v_fmac_f32_e32 v72, v40, v40
	v_fmac_f32_e32 v73, v41, v41
	v_fmac_f32_e32 v72, v42, v42
	v_fmac_f32_e32 v73, v43, v43
	v_fmac_f32_e32 v72, v44, v44
	v_fmac_f32_e32 v73, v45, v45
	v_fmac_f32_e32 v72, v46, v46
	v_fmac_f32_e32 v73, v47, v47
	v_fmac_f32_e32 v72, v48, v48
	v_fmac_f32_e32 v73, v49, v49
	v_fmac_f32_e32 v72, v50, v50
	v_fmac_f32_e32 v73, v51, v51
	v_add_f32_e32 v72, v72, v73
	s_nop 1
	v_add_f32_dpp v72, v72, v72 quad_perm:[1,0,3,2] row_mask:0xf bank_mask:0xf
	s_nop 1
	v_add_f32_dpp v72, v72, v72 quad_perm:[2,3,0,1] row_mask:0xf bank_mask:0xf
	s_nop 1
	v_add_f32_dpp v72, v72, v72 row_half_mirror row_mask:0xf bank_mask:0xf
	s_nop 1
	v_add_f32_dpp v72, v72, v72 row_mirror row_mask:0xf bank_mask:0xf
	s_nop 1
	v_add_f32_dpp v72, v72, v72 row_bcast:15 row_mask:0xa bank_mask:0xf
	s_nop 1
	v_add_f32_dpp v72, v72, v72 row_bcast:31 row_mask:0xc bank_mask:0xf
	s_nop 1
	v_readlane_b32 s3, v72, 63
	s_nop 1
	v_mov_b32_e32 v72, s3
	v_fmamk_f32 v72, v72, 0x3a800000, v172
	v_rsq_f32_e32 v72, v72
	s_nop 0
	v_mul_f32_e32 v36, v36, v72
	v_mul_f32_e32 v37, v37, v72
	v_mul_f32_e32 v38, v38, v72
	v_mul_f32_e32 v39, v39, v72
	v_mul_f32_e32 v36, v4, v36
	v_mul_f32_e32 v37, v5, v37
	v_mul_f32_e32 v38, v6, v38
	v_mul_f32_e32 v39, v7, v39
	v_cvt_pk_bf16_f32 v74, v36, v37
	v_cvt_pk_bf16_f32 v75, v38, v39
	global_store_dwordx2 v71, v[74:75], s[36:37]
	v_mul_f32_e32 v40, v40, v72
	v_mul_f32_e32 v41, v41, v72
	v_mul_f32_e32 v42, v42, v72
	v_mul_f32_e32 v43, v43, v72
	v_mul_f32_e32 v40, v8, v40
	v_mul_f32_e32 v41, v9, v41
	v_mul_f32_e32 v42, v10, v42
	v_mul_f32_e32 v43, v11, v43
	v_cvt_pk_bf16_f32 v76, v40, v41
	v_cvt_pk_bf16_f32 v77, v42, v43
	global_store_dwordx2 v71, v[76:77], s[36:37] offset:512
	v_mul_f32_e32 v44, v44, v72
	v_mul_f32_e32 v45, v45, v72
	v_mul_f32_e32 v46, v46, v72
	v_mul_f32_e32 v47, v47, v72
	v_mul_f32_e32 v44, v12, v44
	v_mul_f32_e32 v45, v13, v45
	v_mul_f32_e32 v46, v14, v46
	v_mul_f32_e32 v47, v15, v47
	v_cvt_pk_bf16_f32 v78, v44, v45
	v_cvt_pk_bf16_f32 v79, v46, v47
	global_store_dwordx2 v71, v[78:79], s[36:37] offset:1024
	v_mul_f32_e32 v48, v48, v72
	v_mul_f32_e32 v49, v49, v72
	v_mul_f32_e32 v50, v50, v72
	v_mul_f32_e32 v51, v51, v72
	v_mul_f32_e32 v48, v16, v48
	v_mul_f32_e32 v49, v17, v49
	v_mul_f32_e32 v50, v18, v50
	v_mul_f32_e32 v51, v19, v51
	v_cvt_pk_bf16_f32 v80, v48, v49
	v_cvt_pk_bf16_f32 v81, v50, v51
	global_store_dwordx2 v71, v[80:81], s[36:37] offset:1536
	s_add_u32 s36, s36, 0x400000
	s_addc_u32 s37, s37, 0
	global_load_dwordx4 v[36:39], v70, s[34:35]
	global_load_dwordx4 v[40:43], v70, s[34:35] offset:1024
	global_load_dwordx4 v[44:47], v70, s[34:35] offset:2048
	global_load_dwordx4 v[48:51], v70, s[34:35] offset:3072
	s_add_u32 s34, s34, 0x800000
	s_addc_u32 s35, s35, 0
	s_waitcnt vmcnt(16)
	v_mul_f32_e32 v72, v52, v52
	v_mul_f32_e32 v73, v53, v53
	v_fmac_f32_e32 v72, v54, v54
	v_fmac_f32_e32 v73, v55, v55
	v_fmac_f32_e32 v72, v56, v56
	v_fmac_f32_e32 v73, v57, v57
	v_fmac_f32_e32 v72, v58, v58
	v_fmac_f32_e32 v73, v59, v59
	v_fmac_f32_e32 v72, v60, v60
	v_fmac_f32_e32 v73, v61, v61
	v_fmac_f32_e32 v72, v62, v62
	v_fmac_f32_e32 v73, v63, v63
	v_fmac_f32_e32 v72, v64, v64
	v_fmac_f32_e32 v73, v65, v65
	v_fmac_f32_e32 v72, v66, v66
	v_fmac_f32_e32 v73, v67, v67
	v_add_f32_e32 v72, v72, v73
	s_nop 1
	v_add_f32_dpp v72, v72, v72 quad_perm:[1,0,3,2] row_mask:0xf bank_mask:0xf
	s_nop 1
	v_add_f32_dpp v72, v72, v72 quad_perm:[2,3,0,1] row_mask:0xf bank_mask:0xf
	s_nop 1
	v_add_f32_dpp v72, v72, v72 row_half_mirror row_mask:0xf bank_mask:0xf
	s_nop 1
	v_add_f32_dpp v72, v72, v72 row_mirror row_mask:0xf bank_mask:0xf
	s_nop 1
	v_add_f32_dpp v72, v72, v72 row_bcast:15 row_mask:0xa bank_mask:0xf
	s_nop 1
	v_add_f32_dpp v72, v72, v72 row_bcast:31 row_mask:0xc bank_mask:0xf
	s_nop 1
	v_readlane_b32 s3, v72, 63
	s_nop 1
	v_mov_b32_e32 v72, s3
	v_fmamk_f32 v72, v72, 0x3a800000, v172
	v_rsq_f32_e32 v72, v72
	s_nop 0
	v_mul_f32_e32 v52, v52, v72
	v_mul_f32_e32 v53, v53, v72
	v_mul_f32_e32 v54, v54, v72
	v_mul_f32_e32 v55, v55, v72
	v_mul_f32_e32 v52, v4, v52
	v_mul_f32_e32 v53, v5, v53
	v_mul_f32_e32 v54, v6, v54
	v_mul_f32_e32 v55, v7, v55
	v_cvt_pk_bf16_f32 v74, v52, v53
	v_cvt_pk_bf16_f32 v75, v54, v55
	global_store_dwordx2 v71, v[74:75], s[36:37]
	v_mul_f32_e32 v56, v56, v72
	v_mul_f32_e32 v57, v57, v72
	v_mul_f32_e32 v58, v58, v72
	v_mul_f32_e32 v59, v59, v72
	v_mul_f32_e32 v56, v8, v56
	v_mul_f32_e32 v57, v9, v57
	v_mul_f32_e32 v58, v10, v58
	v_mul_f32_e32 v59, v11, v59
	v_cvt_pk_bf16_f32 v76, v56, v57
	v_cvt_pk_bf16_f32 v77, v58, v59
	global_store_dwordx2 v71, v[76:77], s[36:37] offset:512
	v_mul_f32_e32 v60, v60, v72
	v_mul_f32_e32 v61, v61, v72
	v_mul_f32_e32 v62, v62, v72
	v_mul_f32_e32 v63, v63, v72
	v_mul_f32_e32 v60, v12, v60
	v_mul_f32_e32 v61, v13, v61
	v_mul_f32_e32 v62, v14, v62
	v_mul_f32_e32 v63, v15, v63
	v_cvt_pk_bf16_f32 v78, v60, v61
	v_cvt_pk_bf16_f32 v79, v62, v63
	global_store_dwordx2 v71, v[78:79], s[36:37] offset:1024
	v_mul_f32_e32 v64, v64, v72
	v_mul_f32_e32 v65, v65, v72
	v_mul_f32_e32 v66, v66, v72
	v_mul_f32_e32 v67, v67, v72
	v_mul_f32_e32 v64, v16, v64
	v_mul_f32_e32 v65, v17, v65
	v_mul_f32_e32 v66, v18, v66
	v_mul_f32_e32 v67, v19, v67
	v_cvt_pk_bf16_f32 v80, v64, v65
	v_cvt_pk_bf16_f32 v81, v66, v67
	global_store_dwordx2 v71, v[80:81], s[36:37] offset:1536
	s_add_u32 s36, s36, 0x400000
	s_addc_u32 s37, s37, 0
	global_load_dwordx4 v[52:55], v70, s[34:35]
	global_load_dwordx4 v[56:59], v70, s[34:35] offset:1024
	global_load_dwordx4 v[60:63], v70, s[34:35] offset:2048
	global_load_dwordx4 v[64:67], v70, s[34:35] offset:3072
	s_add_u32 s34, s34, 0x800000
	s_addc_u32 s35, s35, 0
	s_waitcnt vmcnt(16)
	v_mul_f32_e32 v72, v20, v20
	v_mul_f32_e32 v73, v21, v21
	v_fmac_f32_e32 v72, v22, v22
	v_fmac_f32_e32 v73, v23, v23
	v_fmac_f32_e32 v72, v24, v24
	v_fmac_f32_e32 v73, v25, v25
	v_fmac_f32_e32 v72, v26, v26
	v_fmac_f32_e32 v73, v27, v27
	v_fmac_f32_e32 v72, v28, v28
	v_fmac_f32_e32 v73, v29, v29
	v_fmac_f32_e32 v72, v30, v30
	v_fmac_f32_e32 v73, v31, v31
	v_fmac_f32_e32 v72, v32, v32
	v_fmac_f32_e32 v73, v33, v33
	v_fmac_f32_e32 v72, v34, v34
	v_fmac_f32_e32 v73, v35, v35
	v_add_f32_e32 v72, v72, v73
	s_nop 1
	v_add_f32_dpp v72, v72, v72 quad_perm:[1,0,3,2] row_mask:0xf bank_mask:0xf
	s_nop 1
	v_add_f32_dpp v72, v72, v72 quad_perm:[2,3,0,1] row_mask:0xf bank_mask:0xf
	s_nop 1
	v_add_f32_dpp v72, v72, v72 row_half_mirror row_mask:0xf bank_mask:0xf
	s_nop 1
	v_add_f32_dpp v72, v72, v72 row_mirror row_mask:0xf bank_mask:0xf
	s_nop 1
	v_add_f32_dpp v72, v72, v72 row_bcast:15 row_mask:0xa bank_mask:0xf
	s_nop 1
	v_add_f32_dpp v72, v72, v72 row_bcast:31 row_mask:0xc bank_mask:0xf
	s_nop 1
	v_readlane_b32 s3, v72, 63
	s_nop 1
	v_mov_b32_e32 v72, s3
	v_fmamk_f32 v72, v72, 0x3a800000, v172
	v_rsq_f32_e32 v72, v72
	s_nop 0
	v_mul_f32_e32 v20, v20, v72
	v_mul_f32_e32 v21, v21, v72
	v_mul_f32_e32 v22, v22, v72
	v_mul_f32_e32 v23, v23, v72
	v_mul_f32_e32 v20, v4, v20
	v_mul_f32_e32 v21, v5, v21
	v_mul_f32_e32 v22, v6, v22
	v_mul_f32_e32 v23, v7, v23
	v_cvt_pk_bf16_f32 v74, v20, v21
	v_cvt_pk_bf16_f32 v75, v22, v23
	global_store_dwordx2 v71, v[74:75], s[36:37]
	v_mul_f32_e32 v24, v24, v72
	v_mul_f32_e32 v25, v25, v72
	v_mul_f32_e32 v26, v26, v72
	v_mul_f32_e32 v27, v27, v72
	v_mul_f32_e32 v24, v8, v24
	v_mul_f32_e32 v25, v9, v25
	v_mul_f32_e32 v26, v10, v26
	v_mul_f32_e32 v27, v11, v27
	v_cvt_pk_bf16_f32 v76, v24, v25
	v_cvt_pk_bf16_f32 v77, v26, v27
	global_store_dwordx2 v71, v[76:77], s[36:37] offset:512
	v_mul_f32_e32 v28, v28, v72
	v_mul_f32_e32 v29, v29, v72
	v_mul_f32_e32 v30, v30, v72
	v_mul_f32_e32 v31, v31, v72
	v_mul_f32_e32 v28, v12, v28
	v_mul_f32_e32 v29, v13, v29
	v_mul_f32_e32 v30, v14, v30
	v_mul_f32_e32 v31, v15, v31
	v_cvt_pk_bf16_f32 v78, v28, v29
	v_cvt_pk_bf16_f32 v79, v30, v31
	global_store_dwordx2 v71, v[78:79], s[36:37] offset:1024
	v_mul_f32_e32 v32, v32, v72
	v_mul_f32_e32 v33, v33, v72
	v_mul_f32_e32 v34, v34, v72
	v_mul_f32_e32 v35, v35, v72
	v_mul_f32_e32 v32, v16, v32
	v_mul_f32_e32 v33, v17, v33
	v_mul_f32_e32 v34, v18, v34
	v_mul_f32_e32 v35, v19, v35
	v_cvt_pk_bf16_f32 v80, v32, v33
	v_cvt_pk_bf16_f32 v81, v34, v35
	global_store_dwordx2 v71, v[80:81], s[36:37] offset:1536
	s_add_u32 s36, s36, 0x400000
	s_addc_u32 s37, s37, 0
	global_load_dwordx4 v[20:23], v70, s[34:35]
	global_load_dwordx4 v[24:27], v70, s[34:35] offset:1024
	global_load_dwordx4 v[28:31], v70, s[34:35] offset:2048
	global_load_dwordx4 v[32:35], v70, s[34:35] offset:3072
	s_add_u32 s34, s34, 0x800000
	s_addc_u32 s35, s35, 0
	s_waitcnt vmcnt(16)
	v_mul_f32_e32 v72, v36, v36
	v_mul_f32_e32 v73, v37, v37
	v_fmac_f32_e32 v72, v38, v38
	v_fmac_f32_e32 v73, v39, v39
	v_fmac_f32_e32 v72, v40, v40
	v_fmac_f32_e32 v73, v41, v41
	v_fmac_f32_e32 v72, v42, v42
	v_fmac_f32_e32 v73, v43, v43
	v_fmac_f32_e32 v72, v44, v44
	v_fmac_f32_e32 v73, v45, v45
	v_fmac_f32_e32 v72, v46, v46
	v_fmac_f32_e32 v73, v47, v47
	v_fmac_f32_e32 v72, v48, v48
	v_fmac_f32_e32 v73, v49, v49
	v_fmac_f32_e32 v72, v50, v50
	v_fmac_f32_e32 v73, v51, v51
	v_add_f32_e32 v72, v72, v73
	s_nop 1
	v_add_f32_dpp v72, v72, v72 quad_perm:[1,0,3,2] row_mask:0xf bank_mask:0xf
	s_nop 1
	v_add_f32_dpp v72, v72, v72 quad_perm:[2,3,0,1] row_mask:0xf bank_mask:0xf
	s_nop 1
	v_add_f32_dpp v72, v72, v72 row_half_mirror row_mask:0xf bank_mask:0xf
	s_nop 1
	v_add_f32_dpp v72, v72, v72 row_mirror row_mask:0xf bank_mask:0xf
	s_nop 1
	v_add_f32_dpp v72, v72, v72 row_bcast:15 row_mask:0xa bank_mask:0xf
	s_nop 1
	v_add_f32_dpp v72, v72, v72 row_bcast:31 row_mask:0xc bank_mask:0xf
	s_nop 1
	v_readlane_b32 s3, v72, 63
	s_nop 1
	v_mov_b32_e32 v72, s3
	v_fmamk_f32 v72, v72, 0x3a800000, v172
	v_rsq_f32_e32 v72, v72
	s_nop 0
	v_mul_f32_e32 v36, v36, v72
	v_mul_f32_e32 v37, v37, v72
	v_mul_f32_e32 v38, v38, v72
	v_mul_f32_e32 v39, v39, v72
	v_mul_f32_e32 v36, v4, v36
	v_mul_f32_e32 v37, v5, v37
	v_mul_f32_e32 v38, v6, v38
	v_mul_f32_e32 v39, v7, v39
	v_cvt_pk_bf16_f32 v74, v36, v37
	v_cvt_pk_bf16_f32 v75, v38, v39
	global_store_dwordx2 v71, v[74:75], s[36:37]
	v_mul_f32_e32 v40, v40, v72
	v_mul_f32_e32 v41, v41, v72
	v_mul_f32_e32 v42, v42, v72
	v_mul_f32_e32 v43, v43, v72
	v_mul_f32_e32 v40, v8, v40
	v_mul_f32_e32 v41, v9, v41
	v_mul_f32_e32 v42, v10, v42
	v_mul_f32_e32 v43, v11, v43
	v_cvt_pk_bf16_f32 v76, v40, v41
	v_cvt_pk_bf16_f32 v77, v42, v43
	global_store_dwordx2 v71, v[76:77], s[36:37] offset:512
	v_mul_f32_e32 v44, v44, v72
	v_mul_f32_e32 v45, v45, v72
	v_mul_f32_e32 v46, v46, v72
	v_mul_f32_e32 v47, v47, v72
	v_mul_f32_e32 v44, v12, v44
	v_mul_f32_e32 v45, v13, v45
	v_mul_f32_e32 v46, v14, v46
	v_mul_f32_e32 v47, v15, v47
	v_cvt_pk_bf16_f32 v78, v44, v45
	v_cvt_pk_bf16_f32 v79, v46, v47
	global_store_dwordx2 v71, v[78:79], s[36:37] offset:1024
	v_mul_f32_e32 v48, v48, v72
	v_mul_f32_e32 v49, v49, v72
	v_mul_f32_e32 v50, v50, v72
	v_mul_f32_e32 v51, v51, v72
	v_mul_f32_e32 v48, v16, v48
	v_mul_f32_e32 v49, v17, v49
	v_mul_f32_e32 v50, v18, v50
	v_mul_f32_e32 v51, v19, v51
	v_cvt_pk_bf16_f32 v80, v48, v49
	v_cvt_pk_bf16_f32 v81, v50, v51
	global_store_dwordx2 v71, v[80:81], s[36:37] offset:1536
	s_add_u32 s36, s36, 0x400000
	s_addc_u32 s37, s37, 0
	global_load_dwordx4 v[36:39], v70, s[34:35]
	global_load_dwordx4 v[40:43], v70, s[34:35] offset:1024
	global_load_dwordx4 v[44:47], v70, s[34:35] offset:2048
	global_load_dwordx4 v[48:51], v70, s[34:35] offset:3072
	s_add_u32 s34, s34, 0x800000
	s_addc_u32 s35, s35, 0
	s_waitcnt vmcnt(16)
	v_mul_f32_e32 v72, v52, v52
	v_mul_f32_e32 v73, v53, v53
	v_fmac_f32_e32 v72, v54, v54
	v_fmac_f32_e32 v73, v55, v55
	v_fmac_f32_e32 v72, v56, v56
	v_fmac_f32_e32 v73, v57, v57
	v_fmac_f32_e32 v72, v58, v58
	v_fmac_f32_e32 v73, v59, v59
	v_fmac_f32_e32 v72, v60, v60
	v_fmac_f32_e32 v73, v61, v61
	v_fmac_f32_e32 v72, v62, v62
	v_fmac_f32_e32 v73, v63, v63
	v_fmac_f32_e32 v72, v64, v64
	v_fmac_f32_e32 v73, v65, v65
	v_fmac_f32_e32 v72, v66, v66
	v_fmac_f32_e32 v73, v67, v67
	v_add_f32_e32 v72, v72, v73
	s_nop 1
	v_add_f32_dpp v72, v72, v72 quad_perm:[1,0,3,2] row_mask:0xf bank_mask:0xf
	s_nop 1
	v_add_f32_dpp v72, v72, v72 quad_perm:[2,3,0,1] row_mask:0xf bank_mask:0xf
	s_nop 1
	v_add_f32_dpp v72, v72, v72 row_half_mirror row_mask:0xf bank_mask:0xf
	s_nop 1
	v_add_f32_dpp v72, v72, v72 row_mirror row_mask:0xf bank_mask:0xf
	s_nop 1
	v_add_f32_dpp v72, v72, v72 row_bcast:15 row_mask:0xa bank_mask:0xf
	s_nop 1
	v_add_f32_dpp v72, v72, v72 row_bcast:31 row_mask:0xc bank_mask:0xf
	s_nop 1
	v_readlane_b32 s3, v72, 63
	s_nop 1
	v_mov_b32_e32 v72, s3
	v_fmamk_f32 v72, v72, 0x3a800000, v172
	v_rsq_f32_e32 v72, v72
	s_nop 0
	v_mul_f32_e32 v52, v52, v72
	v_mul_f32_e32 v53, v53, v72
	v_mul_f32_e32 v54, v54, v72
	v_mul_f32_e32 v55, v55, v72
	v_mul_f32_e32 v52, v4, v52
	v_mul_f32_e32 v53, v5, v53
	v_mul_f32_e32 v54, v6, v54
	v_mul_f32_e32 v55, v7, v55
	v_cvt_pk_bf16_f32 v74, v52, v53
	v_cvt_pk_bf16_f32 v75, v54, v55
	global_store_dwordx2 v71, v[74:75], s[36:37]
	v_mul_f32_e32 v56, v56, v72
	v_mul_f32_e32 v57, v57, v72
	v_mul_f32_e32 v58, v58, v72
	v_mul_f32_e32 v59, v59, v72
	v_mul_f32_e32 v56, v8, v56
	v_mul_f32_e32 v57, v9, v57
	v_mul_f32_e32 v58, v10, v58
	v_mul_f32_e32 v59, v11, v59
	v_cvt_pk_bf16_f32 v76, v56, v57
	v_cvt_pk_bf16_f32 v77, v58, v59
	global_store_dwordx2 v71, v[76:77], s[36:37] offset:512
	v_mul_f32_e32 v60, v60, v72
	v_mul_f32_e32 v61, v61, v72
	v_mul_f32_e32 v62, v62, v72
	v_mul_f32_e32 v63, v63, v72
	v_mul_f32_e32 v60, v12, v60
	v_mul_f32_e32 v61, v13, v61
	v_mul_f32_e32 v62, v14, v62
	v_mul_f32_e32 v63, v15, v63
	v_cvt_pk_bf16_f32 v78, v60, v61
	v_cvt_pk_bf16_f32 v79, v62, v63
	global_store_dwordx2 v71, v[78:79], s[36:37] offset:1024
	v_mul_f32_e32 v64, v64, v72
	v_mul_f32_e32 v65, v65, v72
	v_mul_f32_e32 v66, v66, v72
	v_mul_f32_e32 v67, v67, v72
	v_mul_f32_e32 v64, v16, v64
	v_mul_f32_e32 v65, v17, v65
	v_mul_f32_e32 v66, v18, v66
	v_mul_f32_e32 v67, v19, v67
	v_cvt_pk_bf16_f32 v80, v64, v65
	v_cvt_pk_bf16_f32 v81, v66, v67
	global_store_dwordx2 v71, v[80:81], s[36:37] offset:1536
	s_add_u32 s36, s36, 0x400000
	s_addc_u32 s37, s37, 0
	s_cmpk_lt_u32 s0, 0x100
	s_cbranch_scc0 .Lnrm_ffn_nol8
	global_load_dwordx4 v[52:55], v70, s[34:35]
	global_load_dwordx4 v[56:59], v70, s[34:35] offset:1024
	global_load_dwordx4 v[60:63], v70, s[34:35] offset:2048
	global_load_dwordx4 v[64:67], v70, s[34:35] offset:3072
	s_add_u32 s34, s34, 0x800000
	s_addc_u32 s35, s35, 0

.Lnrm_ffn_done:
	s_mov_b64 s[4:5], exec
	s_branch .LBB0_2301
.Lnrm_ffn_orig:
	v_readlane_b32 s0, v249, 5
	v_ashrrev_i32_e32 v2, 6, v2
	s_nop 0
	v_add_u32_e32 v18, s0, v2
	s_movk_i32 s0, 0x4100
	v_cmp_gt_i32_e32 vcc, s0, v18
	s_and_saveexec_b64 s[4:5], vcc
	s_cbranch_execz .LBB0_2301
	s_load_dwordx4 s[0:3], s[6:7], 0x130
	s_load_dwordx2 s[8:9], s[6:7], 0xa8
	v_lshlrev_b32_e32 v0, 2, v0
	v_and_b32_e32 v24, 0xfc, v0
	v_lshlrev_b32_e32 v0, 2, v24
	s_waitcnt lgkmcnt(0)
	s_add_u32 s6, s0, 0x4000000
	s_addc_u32 s7, s1, 0
	s_lshl_b64 s[10:11], s[72:73], 2
	s_add_u32 s8, s8, s10
	s_addc_u32 s9, s9, s11
	global_load_dwordx4 v[2:5], v0, s[8:9]
	global_load_dwordx4 v[6:9], v0, s[8:9] offset:1024
	global_load_dwordx4 v[10:13], v0, s[8:9] offset:2048
	global_load_dwordx4 v[14:17], v0, s[8:9] offset:3072
	v_cmp_lt_i32_e32 vcc, v181, v180
	v_ashrrev_i32_e32 v19, 31, v18
	v_lshlrev_b64 v[22:23], 12, v[18:19]
	v_cndmask_b32_e32 v0, v178, v181, vcc
	v_cmp_lt_i32_e32 vcc, v173, v180
	v_lshlrev_b32_e32 v28, 2, v0
	v_lshl_add_u64 v[22:23], s[0:1], 0, v[22:23]
	v_cndmask_b32_e32 v0, v178, v173, vcc
	v_cmp_lt_i32_e32 vcc, v230, v180
	v_lshlrev_b32_e32 v29, 2, v0
	s_mov_b64 s[0:1], 0
	v_cndmask_b32_e32 v0, v178, v230, vcc
	v_cmp_lt_i32_e32 vcc, v248, v180
	v_lshlrev_b32_e32 v30, 2, v0
	s_nop 0
	v_cndmask_b32_e32 v0, v178, v248, vcc
	v_cmp_lt_i32_e32 vcc, v132, v180
	v_lshlrev_b32_e32 v31, 2, v0
	s_nop 0
	v_cndmask_b32_e32 v0, v178, v132, vcc
	v_cmp_lt_i32_e32 vcc, v186, v180
	v_lshlrev_b32_e32 v32, 2, v0
	s_nop 0
	v_cndmask_b32_e32 v0, v178, v186, vcc
	v_lshlrev_b32_e32 v33, 2, v0
	v_lshlrev_b32_e32 v0, 1, v24
	v_lshl_add_u64 v[20:21], s[2:3], 0, v[0:1]
	v_lshlrev_b32_e32 v0, 2, v24
	s_branch .LBB0_2299

.LBB0_2484:
	s_or_b64 exec, exec, s[0:1]
	s_mov_b64 s[6:7], s[84:85]
	v_mov_b32_e32 v0, v196
	s_waitcnt lgkmcnt(0)
	v_mov_b32_e32 v2, v196
	s_barrier
	v_readlane_b32 s0, v249, 1
	s_nop 0
	s_cmpk_lg_u32 s0, 0x200
	s_cbranch_scc1 .Lnrm_ple_orig
	v_readlane_b32 s0, v249, 5
	v_lshrrev_b32_e32 v68, 6, v196
	s_load_dwordx4 s[28:31], s[84:85], 0x130
	s_load_dwordx2 s[32:33], s[84:85], 0xc0
	v_and_b32_e32 v69, 63, v196
	v_readfirstlane_b32 s1, v68
	v_lshlrev_b32_e32 v70, 4, v69
	v_lshlrev_b32_e32 v71, 3, v69
	s_add_i32 s0, s0, s1
	s_waitcnt lgkmcnt(0)
	s_lshl_b32 s2, s72, 2
	s_add_u32 s32, s32, s2
	s_addc_u32 s33, s33, 0
	global_load_dwordx4 v[4:7], v70, s[32:33]
	global_load_dwordx4 v[8:11], v70, s[32:33] offset:1024
	global_load_dwordx4 v[12:15], v70, s[32:33] offset:2048
	global_load_dwordx4 v[16:19], v70, s[32:33] offset:3072
	s_lshl_b32 s2, s0, 12
	s_add_u32 s34, s28, s2
	s_addc_u32 s35, s29, 0
	s_lshl_b32 s2, s0, 11
	s_add_u32 s36, s30, s2
	s_addc_u32 s37, s31, 0
	global_load_dwordx4 v[20:23], v70, s[34:35]
	global_load_dwordx4 v[24:27], v70, s[34:35] offset:1024
	global_load_dwordx4 v[28:31], v70, s[34:35] offset:2048
	global_load_dwordx4 v[32:35], v70, s[34:35] offset:3072
	s_add_u32 s34, s34, 0x800000
	s_addc_u32 s35, s35, 0
	global_load_dwordx4 v[36:39], v70, s[34:35]
	global_load_dwordx4 v[40:43], v70, s[34:35] offset:1024
	global_load_dwordx4 v[44:47], v70, s[34:35] offset:2048
	global_load_dwordx4 v[48:51], v70, s[34:35] offset:3072
	s_add_u32 s34, s34, 0x800000
	s_addc_u32 s35, s35, 0
	global_load_dwordx4 v[52:55], v70, s[34:35]
	global_load_dwordx4 v[56:59], v70, s[34:35] offset:1024
	global_load_dwordx4 v[60:63], v70, s[34:35] offset:2048
	global_load_dwordx4 v[64:67], v70, s[34:35] offset:3072
	s_add_u32 s34, s34, 0x800000
	s_addc_u32 s35, s35, 0
	s_waitcnt vmcnt(8)
	v_mul_f32_e32 v72, v20, v20
	v_mul_f32_e32 v73, v21, v21
	v_fmac_f32_e32 v72, v22, v22
	v_fmac_f32_e32 v73, v23, v23
	v_fmac_f32_e32 v72, v24, v24
	v_fmac_f32_e32 v73, v25, v25
	v_fmac_f32_e32 v72, v26, v26
	v_fmac_f32_e32 v73, v27, v27
	v_fmac_f32_e32 v72, v28, v28
	v_fmac_f32_e32 v73, v29, v29
	v_fmac_f32_e32 v72, v30, v30
	v_fmac_f32_e32 v73, v31, v31
	v_fmac_f32_e32 v72, v32, v32
	v_fmac_f32_e32 v73, v33, v33
	v_fmac_f32_e32 v72, v34, v34
	v_fmac_f32_e32 v73, v35, v35
	v_add_f32_e32 v72, v72, v73
	s_nop 1
	v_add_f32_dpp v72, v72, v72 quad_perm:[1,0,3,2] row_mask:0xf bank_mask:0xf
	s_nop 1
	v_add_f32_dpp v72, v72, v72 quad_perm:[2,3,0,1] row_mask:0xf bank_mask:0xf
	s_nop 1
	v_add_f32_dpp v72, v72, v72 row_half_mirror row_mask:0xf bank_mask:0xf
	s_nop 1
	v_add_f32_dpp v72, v72, v72 row_mirror row_mask:0xf bank_mask:0xf
	s_nop 1
	v_add_f32_dpp v72, v72, v72 row_bcast:15 row_mask:0xa bank_mask:0xf
	s_nop 1
	v_add_f32_dpp v72, v72, v72 row_bcast:31 row_mask:0xc bank_mask:0xf
	s_nop 1
	v_readlane_b32 s3, v72, 63
	s_nop 1
	v_mov_b32_e32 v72, s3
	v_fmamk_f32 v72, v72, 0x3a800000, v172
	v_rsq_f32_e32 v72, v72
	s_nop 0
	v_mul_f32_e32 v20, v20, v72
	v_mul_f32_e32 v21, v21, v72
	v_mul_f32_e32 v22, v22, v72
	v_mul_f32_e32 v23, v23, v72
	v_mul_f32_e32 v20, v4, v20
	v_mul_f32_e32 v21, v5, v21
	v_mul_f32_e32 v22, v6, v22
	v_mul_f32_e32 v23, v7, v23
	v_cvt_pk_bf16_f32 v74, v20, v21
	v_cvt_pk_bf16_f32 v75, v22, v23
	global_store_dwordx2 v71, v[74:75], s[36:37]
	v_mul_f32_e32 v24, v24, v72
	v_mul_f32_e32 v25, v25, v72
	v_mul_f32_e32 v26, v26, v72
	v_mul_f32_e32 v27, v27, v72
	v_mul_f32_e32 v24, v8, v24
	v_mul_f32_e32 v25, v9, v25
	v_mul_f32_e32 v26, v10, v26
	v_mul_f32_e32 v27, v11, v27
	v_cvt_pk_bf16_f32 v76, v24, v25
	v_cvt_pk_bf16_f32 v77, v26, v27
	global_store_dwordx2 v71, v[76:77], s[36:37] offset:512
	v_mul_f32_e32 v28, v28, v72
	v_mul_f32_e32 v29, v29, v72
	v_mul_f32_e32 v30, v30, v72
	v_mul_f32_e32 v31, v31, v72
	v_mul_f32_e32 v28, v12, v28
	v_mul_f32_e32 v29, v13, v29
	v_mul_f32_e32 v30, v14, v30
	v_mul_f32_e32 v31, v15, v31
	v_cvt_pk_bf16_f32 v78, v28, v29
	v_cvt_pk_bf16_f32 v79, v30, v31
	global_store_dwordx2 v71, v[78:79], s[36:37] offset:1024
	v_mul_f32_e32 v32, v32, v72
	v_mul_f32_e32 v33, v33, v72
	v_mul_f32_e32 v34, v34, v72
	v_mul_f32_e32 v35, v35, v72
	v_mul_f32_e32 v32, v16, v32
	v_mul_f32_e32 v33, v17, v33
	v_mul_f32_e32 v34, v18, v34
	v_mul_f32_e32 v35, v19, v35
	v_cvt_pk_bf16_f32 v80, v32, v33
	v_cvt_pk_bf16_f32 v81, v34, v35
	global_store_dwordx2 v71, v[80:81], s[36:37] offset:1536
	s_add_u32 s36, s36, 0x400000
	s_addc_u32 s37, s37, 0
	global_load_dwordx4 v[20:23], v70, s[34:35]
	global_load_dwordx4 v[24:27], v70, s[34:35] offset:1024
	global_load_dwordx4 v[28:31], v70, s[34:35] offset:2048
	global_load_dwordx4 v[32:35], v70, s[34:35] offset:3072
	s_add_u32 s34, s34, 0x800000
	s_addc_u32 s35, s35, 0
	s_waitcnt vmcnt(12)
	v_mul_f32_e32 v72, v36, v36
	v_mul_f32_e32 v73, v37, v37
	v_fmac_f32_e32 v72, v38, v38
	v_fmac_f32_e32 v73, v39, v39
	v_fmac_f32_e32 v72, v40, v40
	v_fmac_f32_e32 v73, v41, v41
	v_fmac_f32_e32 v72, v42, v42
	v_fmac_f32_e32 v73, v43, v43
	v_fmac_f32_e32 v72, v44, v44
	v_fmac_f32_e32 v73, v45, v45
	v_fmac_f32_e32 v72, v46, v46
	v_fmac_f32_e32 v73, v47, v47
	v_fmac_f32_e32 v72, v48, v48
	v_fmac_f32_e32 v73, v49, v49
	v_fmac_f32_e32 v72, v50, v50
	v_fmac_f32_e32 v73, v51, v51
	v_add_f32_e32 v72, v72, v73
	s_nop 1
	v_add_f32_dpp v72, v72, v72 quad_perm:[1,0,3,2] row_mask:0xf bank_mask:0xf
	s_nop 1
	v_add_f32_dpp v72, v72, v72 quad_perm:[2,3,0,1] row_mask:0xf bank_mask:0xf
	s_nop 1
	v_add_f32_dpp v72, v72, v72 row_half_mirror row_mask:0xf bank_mask:0xf
	s_nop 1
	v_add_f32_dpp v72, v72, v72 row_mirror row_mask:0xf bank_mask:0xf
	s_nop 1
	v_add_f32_dpp v72, v72, v72 row_bcast:15 row_mask:0xa bank_mask:0xf
	s_nop 1
	v_add_f32_dpp v72, v72, v72 row_bcast:31 row_mask:0xc bank_mask:0xf
	s_nop 1
	v_readlane_b32 s3, v72, 63
	s_nop 1
	v_mov_b32_e32 v72, s3
	v_fmamk_f32 v72, v72, 0x3a800000, v172
	v_rsq_f32_e32 v72, v72
	s_nop 0
	v_mul_f32_e32 v36, v36, v72
	v_mul_f32_e32 v37, v37, v72
	v_mul_f32_e32 v38, v38, v72
	v_mul_f32_e32 v39, v39, v72
	v_mul_f32_e32 v36, v4, v36
	v_mul_f32_e32 v37, v5, v37
	v_mul_f32_e32 v38, v6, v38
	v_mul_f32_e32 v39, v7, v39
	v_cvt_pk_bf16_f32 v74, v36, v37
	v_cvt_pk_bf16_f32 v75, v38, v39
	global_store_dwordx2 v71, v[74:75], s[36:37]
	v_mul_f32_e32 v40, v40, v72
	v_mul_f32_e32 v41, v41, v72
	v_mul_f32_e32 v42, v42, v72
	v_mul_f32_e32 v43, v43, v72
	v_mul_f32_e32 v40, v8, v40
	v_mul_f32_e32 v41, v9, v41
	v_mul_f32_e32 v42, v10, v42
	v_mul_f32_e32 v43, v11, v43
	v_cvt_pk_bf16_f32 v76, v40, v41
	v_cvt_pk_bf16_f32 v77, v42, v43
	global_store_dwordx2 v71, v[76:77], s[36:37] offset:512
	v_mul_f32_e32 v44, v44, v72
	v_mul_f32_e32 v45, v45, v72
	v_mul_f32_e32 v46, v46, v72
	v_mul_f32_e32 v47, v47, v72
	v_mul_f32_e32 v44, v12, v44
	v_mul_f32_e32 v45, v13, v45
	v_mul_f32_e32 v46, v14, v46
	v_mul_f32_e32 v47, v15, v47
	v_cvt_pk_bf16_f32 v78, v44, v45
	v_cvt_pk_bf16_f32 v79, v46, v47
	global_store_dwordx2 v71, v[78:79], s[36:37] offset:1024
	v_mul_f32_e32 v48, v48, v72
	v_mul_f32_e32 v49, v49, v72
	v_mul_f32_e32 v50, v50, v72
	v_mul_f32_e32 v51, v51, v72
	v_mul_f32_e32 v48, v16, v48
	v_mul_f32_e32 v49, v17, v49
	v_mul_f32_e32 v50, v18, v50
	v_mul_f32_e32 v51, v19, v51
	v_cvt_pk_bf16_f32 v80, v48, v49
	v_cvt_pk_bf16_f32 v81, v50, v51
	global_store_dwordx2 v71, v[80:81], s[36:37] offset:1536
	s_add_u32 s36, s36, 0x400000
	s_addc_u32 s37, s37, 0
	global_load_dwordx4 v[36:39], v70, s[34:35]
	global_load_dwordx4 v[40:43], v70, s[34:35] offset:1024
	global_load_dwordx4 v[44:47], v70, s[34:35] offset:2048
	global_load_dwordx4 v[48:51], v70, s[34:35] offset:3072
	s_add_u32 s34, s34, 0x800000
	s_addc_u32 s35, s35, 0
	s_waitcnt vmcnt(16)
	v_mul_f32_e32 v72, v52, v52
	v_mul_f32_e32 v73, v53, v53
	v_fmac_f32_e32 v72, v54, v54
	v_fmac_f32_e32 v73, v55, v55
	v_fmac_f32_e32 v72, v56, v56
	v_fmac_f32_e32 v73, v57, v57
	v_fmac_f32_e32 v72, v58, v58
	v_fmac_f32_e32 v73, v59, v59
	v_fmac_f32_e32 v72, v60, v60
	v_fmac_f32_e32 v73, v61, v61
	v_fmac_f32_e32 v72, v62, v62
	v_fmac_f32_e32 v73, v63, v63
	v_fmac_f32_e32 v72, v64, v64
	v_fmac_f32_e32 v73, v65, v65
	v_fmac_f32_e32 v72, v66, v66
	v_fmac_f32_e32 v73, v67, v67
	v_add_f32_e32 v72, v72, v73
	s_nop 1
	v_add_f32_dpp v72, v72, v72 quad_perm:[1,0,3,2] row_mask:0xf bank_mask:0xf
	s_nop 1
	v_add_f32_dpp v72, v72, v72 quad_perm:[2,3,0,1] row_mask:0xf bank_mask:0xf
	s_nop 1
	v_add_f32_dpp v72, v72, v72 row_half_mirror row_mask:0xf bank_mask:0xf
	s_nop 1
	v_add_f32_dpp v72, v72, v72 row_mirror row_mask:0xf bank_mask:0xf
	s_nop 1
	v_add_f32_dpp v72, v72, v72 row_bcast:15 row_mask:0xa bank_mask:0xf
	s_nop 1
	v_add_f32_dpp v72, v72, v72 row_bcast:31 row_mask:0xc bank_mask:0xf
	s_nop 1
	v_readlane_b32 s3, v72, 63
	s_nop 1
	v_mov_b32_e32 v72, s3
	v_fmamk_f32 v72, v72, 0x3a800000, v172
	v_rsq_f32_e32 v72, v72
	s_nop 0
	v_mul_f32_e32 v52, v52, v72
	v_mul_f32_e32 v53, v53, v72
	v_mul_f32_e32 v54, v54, v72
	v_mul_f32_e32 v55, v55, v72
	v_mul_f32_e32 v52, v4, v52
	v_mul_f32_e32 v53, v5, v53
	v_mul_f32_e32 v54, v6, v54
	v_mul_f32_e32 v55, v7, v55
	v_cvt_pk_bf16_f32 v74, v52, v53
	v_cvt_pk_bf16_f32 v75, v54, v55
	global_store_dwordx2 v71, v[74:75], s[36:37]
	v_mul_f32_e32 v56, v56, v72
	v_mul_f32_e32 v57, v57, v72
	v_mul_f32_e32 v58, v58, v72
	v_mul_f32_e32 v59, v59, v72
	v_mul_f32_e32 v56, v8, v56
	v_mul_f32_e32 v57, v9, v57
	v_mul_f32_e32 v58, v10, v58
	v_mul_f32_e32 v59, v11, v59
	v_cvt_pk_bf16_f32 v76, v56, v57
	v_cvt_pk_bf16_f32 v77, v58, v59
	global_store_dwordx2 v71, v[76:77], s[36:37] offset:512
	v_mul_f32_e32 v60, v60, v72
	v_mul_f32_e32 v61, v61, v72
	v_mul_f32_e32 v62, v62, v72
	v_mul_f32_e32 v63, v63, v72
	v_mul_f32_e32 v60, v12, v60
	v_mul_f32_e32 v61, v13, v61
	v_mul_f32_e32 v62, v14, v62
	v_mul_f32_e32 v63, v15, v63
	v_cvt_pk_bf16_f32 v78, v60, v61
	v_cvt_pk_bf16_f32 v79, v62, v63
	global_store_dwordx2 v71, v[78:79], s[36:37] offset:1024
	v_mul_f32_e32 v64, v64, v72
	v_mul_f32_e32 v65, v65, v72
	v_mul_f32_e32 v66, v66, v72
	v_mul_f32_e32 v67, v67, v72
	v_mul_f32_e32 v64, v16, v64
	v_mul_f32_e32 v65, v17, v65
	v_mul_f32_e32 v66, v18, v66
	v_mul_f32_e32 v67, v19, v67
	v_cvt_pk_bf16_f32 v80, v64, v65
	v_cvt_pk_bf16_f32 v81, v66, v67
	global_store_dwordx2 v71, v[80:81], s[36:37] offset:1536
	s_add_u32 s36, s36, 0x400000
	s_addc_u32 s37, s37, 0
	global_load_dwordx4 v[52:55], v70, s[34:35]
	global_load_dwordx4 v[56:59], v70, s[34:35] offset:1024
	global_load_dwordx4 v[60:63], v70, s[34:35] offset:2048
	global_load_dwordx4 v[64:67], v70, s[34:35] offset:3072
	s_add_u32 s34, s34, 0x800000
	s_addc_u32 s35, s35, 0
	s_waitcnt vmcnt(16)
	v_mul_f32_e32 v72, v20, v20
	v_mul_f32_e32 v73, v21, v21
	v_fmac_f32_e32 v72, v22, v22
	v_fmac_f32_e32 v73, v23, v23
	v_fmac_f32_e32 v72, v24, v24
	v_fmac_f32_e32 v73, v25, v25
	v_fmac_f32_e32 v72, v26, v26
	v_fmac_f32_e32 v73, v27, v27
	v_fmac_f32_e32 v72, v28, v28
	v_fmac_f32_e32 v73, v29, v29
	v_fmac_f32_e32 v72, v30, v30
	v_fmac_f32_e32 v73, v31, v31
	v_fmac_f32_e32 v72, v32, v32
	v_fmac_f32_e32 v73, v33, v33
	v_fmac_f32_e32 v72, v34, v34
	v_fmac_f32_e32 v73, v35, v35
	v_add_f32_e32 v72, v72, v73
	s_nop 1
	v_add_f32_dpp v72, v72, v72 quad_perm:[1,0,3,2] row_mask:0xf bank_mask:0xf
	s_nop 1
	v_add_f32_dpp v72, v72, v72 quad_perm:[2,3,0,1] row_mask:0xf bank_mask:0xf
	s_nop 1
	v_add_f32_dpp v72, v72, v72 row_half_mirror row_mask:0xf bank_mask:0xf
	s_nop 1
	v_add_f32_dpp v72, v72, v72 row_mirror row_mask:0xf bank_mask:0xf
	s_nop 1
	v_add_f32_dpp v72, v72, v72 row_bcast:15 row_mask:0xa bank_mask:0xf
	s_nop 1
	v_add_f32_dpp v72, v72, v72 row_bcast:31 row_mask:0xc bank_mask:0xf
	s_nop 1
	v_readlane_b32 s3, v72, 63
	s_nop 1
	v_mov_b32_e32 v72, s3
	v_fmamk_f32 v72, v72, 0x3a800000, v172
	v_rsq_f32_e32 v72, v72
	s_nop 0
	v_mul_f32_e32 v20, v20, v72
	v_mul_f32_e32 v21, v21, v72
	v_mul_f32_e32 v22, v22, v72
	v_mul_f32_e32 v23, v23, v72
	v_mul_f32_e32 v20, v4, v20
	v_mul_f32_e32 v21, v5, v21
	v_mul_f32_e32 v22, v6, v22
	v_mul_f32_e32 v23, v7, v23
	v_cvt_pk_bf16_f32 v74, v20, v21
	v_cvt_pk_bf16_f32 v75, v22, v23
	global_store_dwordx2 v71, v[74:75], s[36:37]
	v_mul_f32_e32 v24, v24, v72
	v_mul_f32_e32 v25, v25, v72
	v_mul_f32_e32 v26, v26, v72
	v_mul_f32_e32 v27, v27, v72
	v_mul_f32_e32 v24, v8, v24
	v_mul_f32_e32 v25, v9, v25
	v_mul_f32_e32 v26, v10, v26
	v_mul_f32_e32 v27, v11, v27
	v_cvt_pk_bf16_f32 v76, v24, v25
	v_cvt_pk_bf16_f32 v77, v26, v27
	global_store_dwordx2 v71, v[76:77], s[36:37] offset:512
	v_mul_f32_e32 v28, v28, v72
	v_mul_f32_e32 v29, v29, v72
	v_mul_f32_e32 v30, v30, v72
	v_mul_f32_e32 v31, v31, v72
	v_mul_f32_e32 v28, v12, v28
	v_mul_f32_e32 v29, v13, v29
	v_mul_f32_e32 v30, v14, v30
	v_mul_f32_e32 v31, v15, v31
	v_cvt_pk_bf16_f32 v78, v28, v29
	v_cvt_pk_bf16_f32 v79, v30, v31
	global_store_dwordx2 v71, v[78:79], s[36:37] offset:1024
	v_mul_f32_e32 v32, v32, v72
	v_mul_f32_e32 v33, v33, v72
	v_mul_f32_e32 v34, v34, v72
	v_mul_f32_e32 v35, v35, v72
	v_mul_f32_e32 v32, v16, v32
	v_mul_f32_e32 v33, v17, v33
	v_mul_f32_e32 v34, v18, v34
	v_mul_f32_e32 v35, v19, v35
	v_cvt_pk_bf16_f32 v80, v32, v33
	v_cvt_pk_bf16_f32 v81, v34, v35
	global_store_dwordx2 v71, v[80:81], s[36:37] offset:1536
	s_add_u32 s36, s36, 0x400000
	s_addc_u32 s37, s37, 0
	global_load_dwordx4 v[20:23], v70, s[34:35]
	global_load_dwordx4 v[24:27], v70, s[34:35] offset:1024
	global_load_dwordx4 v[28:31], v70, s[34:35] offset:2048
	global_load_dwordx4 v[32:35], v70, s[34:35] offset:3072
	s_add_u32 s34, s34, 0x800000
	s_addc_u32 s35, s35, 0
	s_waitcnt vmcnt(16)
	v_mul_f32_e32 v72, v36, v36
	v_mul_f32_e32 v73, v37, v37
	v_fmac_f32_e32 v72, v38, v38
	v_fmac_f32_e32 v73, v39, v39
	v_fmac_f32_e32 v72, v40, v40
	v_fmac_f32_e32 v73, v41, v41
	v_fmac_f32_e32 v72, v42, v42
	v_fmac_f32_e32 v73, v43, v43
	v_fmac_f32_e32 v72, v44, v44
	v_fmac_f32_e32 v73, v45, v45
	v_fmac_f32_e32 v72, v46, v46
	v_fmac_f32_e32 v73, v47, v47
	v_fmac_f32_e32 v72, v48, v48
	v_fmac_f32_e32 v73, v49, v49
	v_fmac_f32_e32 v72, v50, v50
	v_fmac_f32_e32 v73, v51, v51
	v_add_f32_e32 v72, v72, v73
	s_nop 1
	v_add_f32_dpp v72, v72, v72 quad_perm:[1,0,3,2] row_mask:0xf bank_mask:0xf
	s_nop 1
	v_add_f32_dpp v72, v72, v72 quad_perm:[2,3,0,1] row_mask:0xf bank_mask:0xf
	s_nop 1
	v_add_f32_dpp v72, v72, v72 row_half_mirror row_mask:0xf bank_mask:0xf
	s_nop 1
	v_add_f32_dpp v72, v72, v72 row_mirror row_mask:0xf bank_mask:0xf
	s_nop 1
	v_add_f32_dpp v72, v72, v72 row_bcast:15 row_mask:0xa bank_mask:0xf
	s_nop 1
	v_add_f32_dpp v72, v72, v72 row_bcast:31 row_mask:0xc bank_mask:0xf
	s_nop 1
	v_readlane_b32 s3, v72, 63
	s_nop 1
	v_mov_b32_e32 v72, s3
	v_fmamk_f32 v72, v72, 0x3a800000, v172
	v_rsq_f32_e32 v72, v72
	s_nop 0
	v_mul_f32_e32 v36, v36, v72
	v_mul_f32_e32 v37, v37, v72
	v_mul_f32_e32 v38, v38, v72
	v_mul_f32_e32 v39, v39, v72
	v_mul_f32_e32 v36, v4, v36
	v_mul_f32_e32 v37, v5, v37
	v_mul_f32_e32 v38, v6, v38
	v_mul_f32_e32 v39, v7, v39
	v_cvt_pk_bf16_f32 v74, v36, v37
	v_cvt_pk_bf16_f32 v75, v38, v39
	global_store_dwordx2 v71, v[74:75], s[36:37]
	v_mul_f32_e32 v40, v40, v72
	v_mul_f32_e32 v41, v41, v72
	v_mul_f32_e32 v42, v42, v72
	v_mul_f32_e32 v43, v43, v72
	v_mul_f32_e32 v40, v8, v40
	v_mul_f32_e32 v41, v9, v41
	v_mul_f32_e32 v42, v10, v42
	v_mul_f32_e32 v43, v11, v43
	v_cvt_pk_bf16_f32 v76, v40, v41
	v_cvt_pk_bf16_f32 v77, v42, v43
	global_store_dwordx2 v71, v[76:77], s[36:37] offset:512
	v_mul_f32_e32 v44, v44, v72
	v_mul_f32_e32 v45, v45, v72
	v_mul_f32_e32 v46, v46, v72
	v_mul_f32_e32 v47, v47, v72
	v_mul_f32_e32 v44, v12, v44
	v_mul_f32_e32 v45, v13, v45
	v_mul_f32_e32 v46, v14, v46
	v_mul_f32_e32 v47, v15, v47
	v_cvt_pk_bf16_f32 v78, v44, v45
	v_cvt_pk_bf16_f32 v79, v46, v47
	global_store_dwordx2 v71, v[78:79], s[36:37] offset:1024
	v_mul_f32_e32 v48, v48, v72
	v_mul_f32_e32 v49, v49, v72
	v_mul_f32_e32 v50, v50, v72
	v_mul_f32_e32 v51, v51, v72
	v_mul_f32_e32 v48, v16, v48
	v_mul_f32_e32 v49, v17, v49
	v_mul_f32_e32 v50, v18, v50
	v_mul_f32_e32 v51, v19, v51
	v_cvt_pk_bf16_f32 v80, v48, v49
	v_cvt_pk_bf16_f32 v81, v50, v51
	global_store_dwordx2 v71, v[80:81], s[36:37] offset:1536
	s_add_u32 s36, s36, 0x400000
	s_addc_u32 s37, s37, 0
	global_load_dwordx4 v[36:39], v70, s[34:35]
	global_load_dwordx4 v[40:43], v70, s[34:35] offset:1024
	global_load_dwordx4 v[44:47], v70, s[34:35] offset:2048
	global_load_dwordx4 v[48:51], v70, s[34:35] offset:3072
	s_add_u32 s34, s34, 0x800000
	s_addc_u32 s35, s35, 0
	s_waitcnt vmcnt(16)
	v_mul_f32_e32 v72, v52, v52
	v_mul_f32_e32 v73, v53, v53
	v_fmac_f32_e32 v72, v54, v54
	v_fmac_f32_e32 v73, v55, v55
	v_fmac_f32_e32 v72, v56, v56
	v_fmac_f32_e32 v73, v57, v57
	v_fmac_f32_e32 v72, v58, v58
	v_fmac_f32_e32 v73, v59, v59
	v_fmac_f32_e32 v72, v60, v60
	v_fmac_f32_e32 v73, v61, v61
	v_fmac_f32_e32 v72, v62, v62
	v_fmac_f32_e32 v73, v63, v63
	v_fmac_f32_e32 v72, v64, v64
	v_fmac_f32_e32 v73, v65, v65
	v_fmac_f32_e32 v72, v66, v66
	v_fmac_f32_e32 v73, v67, v67
	v_add_f32_e32 v72, v72, v73
	s_nop 1
	v_add_f32_dpp v72, v72, v72 quad_perm:[1,0,3,2] row_mask:0xf bank_mask:0xf
	s_nop 1
	v_add_f32_dpp v72, v72, v72 quad_perm:[2,3,0,1] row_mask:0xf bank_mask:0xf
	s_nop 1
	v_add_f32_dpp v72, v72, v72 row_half_mirror row_mask:0xf bank_mask:0xf
	s_nop 1
	v_add_f32_dpp v72, v72, v72 row_mirror row_mask:0xf bank_mask:0xf
	s_nop 1
	v_add_f32_dpp v72, v72, v72 row_bcast:15 row_mask:0xa bank_mask:0xf
	s_nop 1
	v_add_f32_dpp v72, v72, v72 row_bcast:31 row_mask:0xc bank_mask:0xf
	s_nop 1
	v_readlane_b32 s3, v72, 63
	s_nop 1
	v_mov_b32_e32 v72, s3
	v_fmamk_f32 v72, v72, 0x3a800000, v172
	v_rsq_f32_e32 v72, v72
	s_nop 0
	v_mul_f32_e32 v52, v52, v72
	v_mul_f32_e32 v53, v53, v72
	v_mul_f32_e32 v54, v54, v72
	v_mul_f32_e32 v55, v55, v72
	v_mul_f32_e32 v52, v4, v52
	v_mul_f32_e32 v53, v5, v53
	v_mul_f32_e32 v54, v6, v54
	v_mul_f32_e32 v55, v7, v55
	v_cvt_pk_bf16_f32 v74, v52, v53
	v_cvt_pk_bf16_f32 v75, v54, v55
	global_store_dwordx2 v71, v[74:75], s[36:37]
	v_mul_f32_e32 v56, v56, v72
	v_mul_f32_e32 v57, v57, v72
	v_mul_f32_e32 v58, v58, v72
	v_mul_f32_e32 v59, v59, v72
	v_mul_f32_e32 v56, v8, v56
	v_mul_f32_e32 v57, v9, v57
	v_mul_f32_e32 v58, v10, v58
	v_mul_f32_e32 v59, v11, v59
	v_cvt_pk_bf16_f32 v76, v56, v57
	v_cvt_pk_bf16_f32 v77, v58, v59
	global_store_dwordx2 v71, v[76:77], s[36:37] offset:512
	v_mul_f32_e32 v60, v60, v72
	v_mul_f32_e32 v61, v61, v72
	v_mul_f32_e32 v62, v62, v72
	v_mul_f32_e32 v63, v63, v72
	v_mul_f32_e32 v60, v12, v60
	v_mul_f32_e32 v61, v13, v61
	v_mul_f32_e32 v62, v14, v62
	v_mul_f32_e32 v63, v15, v63
	v_cvt_pk_bf16_f32 v78, v60, v61
	v_cvt_pk_bf16_f32 v79, v62, v63
	global_store_dwordx2 v71, v[78:79], s[36:37] offset:1024
	v_mul_f32_e32 v64, v64, v72
	v_mul_f32_e32 v65, v65, v72
	v_mul_f32_e32 v66, v66, v72
	v_mul_f32_e32 v67, v67, v72
	v_mul_f32_e32 v64, v16, v64
	v_mul_f32_e32 v65, v17, v65
	v_mul_f32_e32 v66, v18, v66
	v_mul_f32_e32 v67, v19, v67
	v_cvt_pk_bf16_f32 v80, v64, v65
	v_cvt_pk_bf16_f32 v81, v66, v67
	global_store_dwordx2 v71, v[80:81], s[36:37] offset:1536
	s_add_u32 s36, s36, 0x400000
	s_addc_u32 s37, s37, 0
	s_cmpk_lt_u32 s0, 0x100
	s_cbranch_scc0 .Lnrm_ple_nol8
	global_load_dwordx4 v[52:55], v70, s[34:35]
	global_load_dwordx4 v[56:59], v70, s[34:35] offset:1024
	global_load_dwordx4 v[60:63], v70, s[34:35] offset:2048
	global_load_dwordx4 v[64:67], v70, s[34:35] offset:3072
	s_add_u32 s34, s34, 0x800000
	s_addc_u32 s35, s35, 0

.Lnrm_ple_orig:
	v_readlane_b32 s0, v249, 5
	v_ashrrev_i32_e32 v2, 6, v2
	s_nop 0
	v_add_u32_e32 v18, s0, v2
	s_movk_i32 s0, 0x4100
	v_cmp_gt_i32_e32 vcc, s0, v18
	s_and_saveexec_b64 s[4:5], vcc
	s_cbranch_execz .LBB0_2489
	s_load_dwordx4 s[0:3], s[6:7], 0x130
	s_load_dwordx2 s[8:9], s[6:7], 0xc0
	v_lshlrev_b32_e32 v0, 2, v0
	v_and_b32_e32 v24, 0xfc, v0
	v_lshlrev_b32_e32 v0, 2, v24
	s_waitcnt lgkmcnt(0)
	s_add_u32 s6, s0, 0x4000000
	s_addc_u32 s7, s1, 0
	s_lshl_b64 s[10:11], s[72:73], 2
	s_add_u32 s8, s8, s10
	s_addc_u32 s9, s9, s11
	global_load_dwordx4 v[2:5], v0, s[8:9]
	global_load_dwordx4 v[6:9], v0, s[8:9] offset:1024
	global_load_dwordx4 v[10:13], v0, s[8:9] offset:2048
	global_load_dwordx4 v[14:17], v0, s[8:9] offset:3072
	v_cmp_lt_i32_e32 vcc, v181, v180
	v_ashrrev_i32_e32 v19, 31, v18
	v_lshlrev_b64 v[22:23], 12, v[18:19]
	v_cndmask_b32_e32 v0, v178, v181, vcc
	v_cmp_lt_i32_e32 vcc, v173, v180
	v_lshlrev_b32_e32 v28, 2, v0
	v_lshl_add_u64 v[22:23], s[0:1], 0, v[22:23]
	v_cndmask_b32_e32 v0, v178, v173, vcc
	v_cmp_lt_i32_e32 vcc, v230, v180
	v_lshlrev_b32_e32 v29, 2, v0
	s_mov_b64 s[0:1], 0
	v_cndmask_b32_e32 v0, v178, v230, vcc
	v_cmp_lt_i32_e32 vcc, v248, v180
	v_lshlrev_b32_e32 v30, 2, v0
	s_nop 0
	v_cndmask_b32_e32 v0, v178, v248, vcc
	v_cmp_lt_i32_e32 vcc, v132, v180
	v_lshlrev_b32_e32 v31, 2, v0
	s_nop 0
	v_cndmask_b32_e32 v0, v178, v132, vcc
	v_cmp_lt_i32_e32 vcc, v186, v180
	v_lshlrev_b32_e32 v32, 2, v0
	s_nop 0
	v_cndmask_b32_e32 v0, v178, v186, vcc
	v_lshlrev_b32_e32 v33, 2, v0
	v_lshlrev_b32_e32 v0, 1, v24
	v_lshl_add_u64 v[20:21], s[2:3], 0, v[0:1]
	v_lshlrev_b32_e32 v0, 2, v24
	s_branch .LBB0_2487
